# v24 + pool-operand phase hand-rewritten with the x row rstd computed inside it (WG = 64-row chunk, per-batch LDS exchange of row sums of squares); the prologue's separate 268 MB pass over x removed
# speedup vs baseline: 1.0032x; 1.0017x over previous
.LBB0_433:
	s_cmpk_gt_i32 s26, 0x3fff
	s_branch .LBB0_438
	s_ashr_i32 s5, s28, 31
	s_ashr_i32 s6, s27, 31
	s_add_u32 s10, s28, s27
	s_addc_u32 s11, s5, s6
	s_lshl_b64 s[6:7], s[10:11], 2
	s_add_u32 s2, s2, s6
	s_addc_u32 s3, s3, s7
	s_add_u32 s6, s2, 0x39400000
	v_readlane_b32 s36, v251, 16
	s_addc_u32 s7, s3, 0
	s_ashr_i32 s5, s4, 31
	v_readlane_b32 s37, v251, 17
	s_lshl_b64 s[8:9], s[4:5], 2
	s_lshl_b64 s[2:3], s[10:11], 14
	s_mov_b64 s[16:17], s[36:37]
	s_add_u32 s2, s16, s2
	v_mov_b32_e32 v3, 0
	s_addc_u32 s3, s17, s3
	v_cmp_eq_u32_e64 s[0:1], 0, v1
	v_lshl_add_u64 v[2:3], s[2:3], 0, v[2:3]
	s_lshl_b64 s[10:11], s[4:5], 14
	s_movk_i32 s5, 0x1000
	s_movk_i32 s14, 0x2000
	s_movk_i32 s15, 0x3000
	v_mov_b32_e32 v1, 0x358637bd
	s_mov_b32 s16, 0xf800000
	v_mov_b32_e32 v4, 0x260
	v_readlane_b32 s38, v251, 18
	v_readlane_b32 s39, v251, 19
	v_readlane_b32 s40, v251, 20
	v_readlane_b32 s41, v251, 21
	v_readlane_b32 s42, v251, 22
	v_readlane_b32 s43, v251, 23
	v_readlane_b32 s44, v251, 24
	v_readlane_b32 s45, v251, 25
	v_readlane_b32 s46, v251, 26
	v_readlane_b32 s47, v251, 27
	v_readlane_b32 s48, v251, 28
	v_readlane_b32 s49, v251, 29
	v_readlane_b32 s50, v251, 30
	v_readlane_b32 s51, v251, 31
	s_branch .LBB0_436

.Lp1f_entry:
	v_readlane_b32 s8, v251, 48
	v_readlane_b32 s9, v251, 54
	v_readlane_b32 s2, v251, 16
	v_readlane_b32 s3, v251, 17
	v_readlane_b32 s6, v251, 20
	v_readlane_b32 s7, v251, 21
	v_readlane_b32 s4, v251, 2
	v_readlane_b32 s5, v251, 3
	s_nop 1
	s_lshr_b32 s9, s9, 6
	s_lshl_b32 s10, s8, 6
	s_and_b32 s11, s10, 0x1fff
	s_lshr_b32 s52, s9, 1
	s_lshl_b32 s12, 2, s52
	s_lshl_b32 s52, s9, 11
	s_add_u32 s2, s2, s52
	s_addc_u32 s3, s3, 0
	s_add_u32 s6, s6, s52
	s_addc_u32 s7, s7, 0
	s_add_u32 s4, s4, 0x29000000
	s_addc_u32 s5, s5, 0
	s_lshl_b32 s52, s9, 10
	s_add_u32 s4, s4, s52
	s_addc_u32 s5, s5, 0
	v_mbcnt_lo_u32_b32 v1, -1, 0
	v_mbcnt_hi_u32_b32 v1, -1, v1
	v_lshlrev_b32_e32 v3, 3, v1
	v_lshlrev_b32_e32 v1, 4, v1
	global_load_dwordx4 v[4:7], v1, s[6:7]
	global_load_dwordx4 v[8:11], v1, s[6:7] offset:1024
	v_mov_b32_e32 v208, 0
	v_mov_b32_e32 v209, 0
	v_mov_b32_e32 v210, 0
	v_mov_b32_e32 v211, 0
	v_mov_b32_e32 v212, 0
	v_mov_b32_e32 v213, 0
	v_mov_b32_e32 v214, 0
	v_mov_b32_e32 v215, 0
	s_cmp_eq_u32 s11, 0
	s_cbranch_scc1 .Lp1f_nohalo
	s_mov_b32 s13, 0
	s_sub_i32 s14, s10, 16
	s_sub_i32 s15, s11, 16
	s_add_i32 s52, s14, 0
	s_mov_b32 s53, 0
	s_lshl_b64 s[52:53], s[52:53], 14
	s_add_u32 s52, s52, s2
	s_addc_u32 s53, s53, s3
	global_load_dwordx4 v[16:19], v1, s[52:53]
	global_load_dwordx4 v[20:23], v1, s[52:53] offset:1024
	s_add_i32 s52, s14, 1
	s_mov_b32 s53, 0
	s_lshl_b64 s[52:53], s[52:53], 14
	s_add_u32 s52, s52, s2
	s_addc_u32 s53, s53, s3
	global_load_dwordx4 v[24:27], v1, s[52:53]
	global_load_dwordx4 v[28:31], v1, s[52:53] offset:1024
	s_add_i32 s52, s14, 2
	s_mov_b32 s53, 0
	s_lshl_b64 s[52:53], s[52:53], 14
	s_add_u32 s52, s52, s2
	s_addc_u32 s53, s53, s3
	global_load_dwordx4 v[32:35], v1, s[52:53]
	global_load_dwordx4 v[36:39], v1, s[52:53] offset:1024
	s_add_i32 s52, s14, 3
	s_mov_b32 s53, 0
	s_lshl_b64 s[52:53], s[52:53], 14
	s_add_u32 s52, s52, s2
	s_addc_u32 s53, s53, s3
	global_load_dwordx4 v[40:43], v1, s[52:53]
	global_load_dwordx4 v[44:47], v1, s[52:53] offset:1024
	s_add_i32 s52, s14, 4
	s_mov_b32 s53, 0
	s_lshl_b64 s[52:53], s[52:53], 14
	s_add_u32 s52, s52, s2
	s_addc_u32 s53, s53, s3
	global_load_dwordx4 v[48:51], v1, s[52:53]
	global_load_dwordx4 v[52:55], v1, s[52:53] offset:1024
	s_add_i32 s52, s14, 5
	s_mov_b32 s53, 0
	s_lshl_b64 s[52:53], s[52:53], 14
	s_add_u32 s52, s52, s2
	s_addc_u32 s53, s53, s3
	global_load_dwordx4 v[56:59], v1, s[52:53]
	global_load_dwordx4 v[60:63], v1, s[52:53] offset:1024
	s_add_i32 s52, s14, 6
	s_mov_b32 s53, 0
	s_lshl_b64 s[52:53], s[52:53], 14
	s_add_u32 s52, s52, s2
	s_addc_u32 s53, s53, s3
	global_load_dwordx4 v[64:67], v1, s[52:53]
	global_load_dwordx4 v[68:71], v1, s[52:53] offset:1024
	s_add_i32 s52, s14, 7
	s_mov_b32 s53, 0
	s_lshl_b64 s[52:53], s[52:53], 14
	s_add_u32 s52, s52, s2
	s_addc_u32 s53, s53, s3
	global_load_dwordx4 v[72:75], v1, s[52:53]
	global_load_dwordx4 v[76:79], v1, s[52:53] offset:1024
	s_waitcnt vmcnt(0)
	v_mul_f32_e32 v80, v16, v16
	v_fmac_f32_e32 v80, v17, v17
	v_fmac_f32_e32 v80, v18, v18
	v_fmac_f32_e32 v80, v19, v19
	v_fmac_f32_e32 v80, v20, v20
	v_fmac_f32_e32 v80, v21, v21
	v_fmac_f32_e32 v80, v22, v22
	v_fmac_f32_e32 v80, v23, v23
	v_mul_f32_e32 v81, v24, v24
	v_fmac_f32_e32 v81, v25, v25
	v_fmac_f32_e32 v81, v26, v26
	v_fmac_f32_e32 v81, v27, v27
	v_fmac_f32_e32 v81, v28, v28
	v_fmac_f32_e32 v81, v29, v29
	v_fmac_f32_e32 v81, v30, v30
	v_fmac_f32_e32 v81, v31, v31
	v_mul_f32_e32 v82, v32, v32
	v_fmac_f32_e32 v82, v33, v33
	v_fmac_f32_e32 v82, v34, v34
	v_fmac_f32_e32 v82, v35, v35
	v_fmac_f32_e32 v82, v36, v36
	v_fmac_f32_e32 v82, v37, v37
	v_fmac_f32_e32 v82, v38, v38
	v_fmac_f32_e32 v82, v39, v39
	v_mul_f32_e32 v83, v40, v40
	v_fmac_f32_e32 v83, v41, v41
	v_fmac_f32_e32 v83, v42, v42
	v_fmac_f32_e32 v83, v43, v43
	v_fmac_f32_e32 v83, v44, v44
	v_fmac_f32_e32 v83, v45, v45
	v_fmac_f32_e32 v83, v46, v46
	v_fmac_f32_e32 v83, v47, v47
	v_mul_f32_e32 v84, v48, v48
	v_fmac_f32_e32 v84, v49, v49
	v_fmac_f32_e32 v84, v50, v50
	v_fmac_f32_e32 v84, v51, v51
	v_fmac_f32_e32 v84, v52, v52
	v_fmac_f32_e32 v84, v53, v53
	v_fmac_f32_e32 v84, v54, v54
	v_fmac_f32_e32 v84, v55, v55
	v_mul_f32_e32 v85, v56, v56
	v_fmac_f32_e32 v85, v57, v57
	v_fmac_f32_e32 v85, v58, v58
	v_fmac_f32_e32 v85, v59, v59
	v_fmac_f32_e32 v85, v60, v60
	v_fmac_f32_e32 v85, v61, v61
	v_fmac_f32_e32 v85, v62, v62
	v_fmac_f32_e32 v85, v63, v63
	v_mul_f32_e32 v86, v64, v64
	v_fmac_f32_e32 v86, v65, v65
	v_fmac_f32_e32 v86, v66, v66
	v_fmac_f32_e32 v86, v67, v67
	v_fmac_f32_e32 v86, v68, v68
	v_fmac_f32_e32 v86, v69, v69
	v_fmac_f32_e32 v86, v70, v70
	v_fmac_f32_e32 v86, v71, v71
	v_mul_f32_e32 v87, v72, v72
	v_fmac_f32_e32 v87, v73, v73
	v_fmac_f32_e32 v87, v74, v74
	v_fmac_f32_e32 v87, v75, v75
	v_fmac_f32_e32 v87, v76, v76
	v_fmac_f32_e32 v87, v77, v77
	v_fmac_f32_e32 v87, v78, v78
	v_fmac_f32_e32 v87, v79, v79
	s_nop 1
	v_add_f32_dpp v80, v80, v80 quad_perm:[1,0,3,2] row_mask:0xf bank_mask:0xf bound_ctrl:1
	v_add_f32_dpp v81, v81, v81 quad_perm:[1,0,3,2] row_mask:0xf bank_mask:0xf bound_ctrl:1
	v_add_f32_dpp v82, v82, v82 quad_perm:[1,0,3,2] row_mask:0xf bank_mask:0xf bound_ctrl:1
	v_add_f32_dpp v83, v83, v83 quad_perm:[1,0,3,2] row_mask:0xf bank_mask:0xf bound_ctrl:1
	v_add_f32_dpp v84, v84, v84 quad_perm:[1,0,3,2] row_mask:0xf bank_mask:0xf bound_ctrl:1
	v_add_f32_dpp v85, v85, v85 quad_perm:[1,0,3,2] row_mask:0xf bank_mask:0xf bound_ctrl:1
	v_add_f32_dpp v86, v86, v86 quad_perm:[1,0,3,2] row_mask:0xf bank_mask:0xf bound_ctrl:1
	v_add_f32_dpp v87, v87, v87 quad_perm:[1,0,3,2] row_mask:0xf bank_mask:0xf bound_ctrl:1
	s_nop 1
	v_add_f32_dpp v80, v80, v80 quad_perm:[2,3,0,1] row_mask:0xf bank_mask:0xf bound_ctrl:1
	v_add_f32_dpp v81, v81, v81 quad_perm:[2,3,0,1] row_mask:0xf bank_mask:0xf bound_ctrl:1
	v_add_f32_dpp v82, v82, v82 quad_perm:[2,3,0,1] row_mask:0xf bank_mask:0xf bound_ctrl:1
	v_add_f32_dpp v83, v83, v83 quad_perm:[2,3,0,1] row_mask:0xf bank_mask:0xf bound_ctrl:1
	v_add_f32_dpp v84, v84, v84 quad_perm:[2,3,0,1] row_mask:0xf bank_mask:0xf bound_ctrl:1
	v_add_f32_dpp v85, v85, v85 quad_perm:[2,3,0,1] row_mask:0xf bank_mask:0xf bound_ctrl:1
	v_add_f32_dpp v86, v86, v86 quad_perm:[2,3,0,1] row_mask:0xf bank_mask:0xf bound_ctrl:1
	v_add_f32_dpp v87, v87, v87 quad_perm:[2,3,0,1] row_mask:0xf bank_mask:0xf bound_ctrl:1
	s_nop 1
	v_add_f32_dpp v80, v80, v80 row_half_mirror row_mask:0xf bank_mask:0xf bound_ctrl:1
	v_add_f32_dpp v81, v81, v81 row_half_mirror row_mask:0xf bank_mask:0xf bound_ctrl:1
	v_add_f32_dpp v82, v82, v82 row_half_mirror row_mask:0xf bank_mask:0xf bound_ctrl:1
	v_add_f32_dpp v83, v83, v83 row_half_mirror row_mask:0xf bank_mask:0xf bound_ctrl:1
	v_add_f32_dpp v84, v84, v84 row_half_mirror row_mask:0xf bank_mask:0xf bound_ctrl:1
	v_add_f32_dpp v85, v85, v85 row_half_mirror row_mask:0xf bank_mask:0xf bound_ctrl:1
	v_add_f32_dpp v86, v86, v86 row_half_mirror row_mask:0xf bank_mask:0xf bound_ctrl:1
	v_add_f32_dpp v87, v87, v87 row_half_mirror row_mask:0xf bank_mask:0xf bound_ctrl:1
	s_nop 1
	v_add_f32_dpp v80, v80, v80 row_mirror row_mask:0xf bank_mask:0xf bound_ctrl:1
	v_add_f32_dpp v81, v81, v81 row_mirror row_mask:0xf bank_mask:0xf bound_ctrl:1
	v_add_f32_dpp v82, v82, v82 row_mirror row_mask:0xf bank_mask:0xf bound_ctrl:1
	v_add_f32_dpp v83, v83, v83 row_mirror row_mask:0xf bank_mask:0xf bound_ctrl:1
	v_add_f32_dpp v84, v84, v84 row_mirror row_mask:0xf bank_mask:0xf bound_ctrl:1
	v_add_f32_dpp v85, v85, v85 row_mirror row_mask:0xf bank_mask:0xf bound_ctrl:1
	v_add_f32_dpp v86, v86, v86 row_mirror row_mask:0xf bank_mask:0xf bound_ctrl:1
	v_add_f32_dpp v87, v87, v87 row_mirror row_mask:0xf bank_mask:0xf bound_ctrl:1
	v_lshrrev_b32_e32 v12, 6, v1
	v_and_b32_e32 v12, 12, v12
	s_lshl_b32 s52, s9, 4
	s_add_i32 s52, s52, 0
	v_add_u32_e32 v12, s52, v12
	s_mov_b32 exec_lo, 0x10001
	s_mov_b32 exec_hi, 0x10001
	ds_write_b32 v12, v80
	ds_write_b32 v12, v81 offset:128
	ds_write_b32 v12, v82 offset:256
	ds_write_b32 v12, v83 offset:384
	ds_write_b32 v12, v84 offset:512
	ds_write_b32 v12, v85 offset:640
	ds_write_b32 v12, v86 offset:768
	ds_write_b32 v12, v87 offset:896
	s_mov_b64 exec, -1
	s_waitcnt lgkmcnt(0)
	s_barrier
	v_lshrrev_b32_e32 v13, 4, v1
	v_and_b32_e32 v13, 7, v13
	v_lshlrev_b32_e32 v12, 7, v13
	ds_read_b128 v[88:91], v12
	ds_read_b128 v[92:95], v12 offset:16
	ds_read_b128 v[96:99], v12 offset:32
	ds_read_b128 v[100:103], v12 offset:48
	ds_read_b128 v[104:107], v12 offset:64
	ds_read_b128 v[108:111], v12 offset:80
	ds_read_b128 v[112:115], v12 offset:96
	ds_read_b128 v[116:119], v12 offset:112
	s_waitcnt lgkmcnt(0)
	v_add_f32_e32 v14, v88, v89
	v_add_f32_e32 v14, v14, v90
	v_add_f32_e32 v14, v14, v91
	v_add_f32_e32 v14, v14, v92
	v_add_f32_e32 v14, v14, v93
	v_add_f32_e32 v14, v14, v94
	v_add_f32_e32 v14, v14, v95
	v_add_f32_e32 v14, v14, v96
	v_add_f32_e32 v14, v14, v97
	v_add_f32_e32 v14, v14, v98
	v_add_f32_e32 v14, v14, v99
	v_add_f32_e32 v14, v14, v100
	v_add_f32_e32 v14, v14, v101
	v_add_f32_e32 v14, v14, v102
	v_add_f32_e32 v14, v14, v103
	v_add_f32_e32 v14, v14, v104
	v_add_f32_e32 v14, v14, v105
	v_add_f32_e32 v14, v14, v106
	v_add_f32_e32 v14, v14, v107
	v_add_f32_e32 v14, v14, v108
	v_add_f32_e32 v14, v14, v109
	v_add_f32_e32 v14, v14, v110
	v_add_f32_e32 v14, v14, v111
	v_add_f32_e32 v14, v14, v112
	v_add_f32_e32 v14, v14, v113
	v_add_f32_e32 v14, v14, v114
	v_add_f32_e32 v14, v14, v115
	v_add_f32_e32 v14, v14, v116
	v_add_f32_e32 v14, v14, v117
	v_add_f32_e32 v14, v14, v118
	v_add_f32_e32 v14, v14, v119
	v_mov_b32_e32 v221, 0x358637bd
	v_mov_b32_e32 v222, 0x260
	s_mov_b32 s54, 0xf800000
	v_fmamk_f32 v14, v14, 0x39800000, v221
	v_mul_f32_e32 v15, 0x4f800000, v14
	v_cmp_gt_f32_e32 vcc, s54, v14
	s_nop 1
	v_cndmask_b32_e32 v14, v14, v15, vcc
	v_sqrt_f32_e32 v15, v14
	s_nop 0
	v_add_u32_e32 v216, -1, v15
	v_add_u32_e32 v217, 1, v15
	v_fma_f32 v218, -v216, v15, v14
	v_fma_f32 v220, -v217, v15, v14
	v_cmp_ge_f32_e64 s[30:31], 0, v218
	s_nop 1
	v_cndmask_b32_e64 v15, v15, v216, s[30:31]
	v_cmp_lt_f32_e64 s[30:31], 0, v220
	s_nop 1
	v_cndmask_b32_e64 v15, v15, v217, s[30:31]
	v_mul_f32_e32 v216, 0x37800000, v15
	v_cndmask_b32_e32 v15, v15, v216, vcc
	v_cmp_class_f32_e32 vcc, v14, v222
	s_nop 1
	v_cndmask_b32_e32 v14, v15, v14, vcc
	v_div_scale_f32 v15, s[30:31], v14, v14, 1.0
	v_rcp_f32_e32 v216, v15
	v_div_scale_f32 v217, vcc, 1.0, v14, 1.0
	v_fma_f32 v218, -v15, v216, 1.0
	v_fmac_f32_e32 v216, v218, v216
	v_mul_f32_e32 v218, v217, v216
	v_fma_f32 v220, -v15, v218, v217
	v_fmac_f32_e32 v218, v220, v216
	v_fma_f32 v15, -v15, v218, v217
	v_div_fmas_f32 v15, v15, v216, v218
	v_div_fixup_f32 v14, v15, v14, 1.0
	s_mul_i32 s52, s9, 320
	s_lshl_b32 s53, s13, 5
	s_add_i32 s52, s52, s53
	s_add_i32 s52, s52, 0x800
	v_lshl_add_u32 v12, v13, 2, s52
	ds_write_b32 v12, v14
	s_lshl_b32 s53, s13, 3
	s_sub_i32 s53, 16, s53
	v_sub_u32_e32 v15, s53, v13
	v_cmp_ge_u32_e32 vcc, s12, v15
	s_nop 1
	v_cndmask_b32_e32 v14, 0, v14, vcc
	s_nop 1
	v_readlane_b32 s20, v14, 0
	v_readlane_b32 s21, v14, 1
	v_readlane_b32 s22, v14, 2
	v_readlane_b32 s23, v14, 3
	v_readlane_b32 s24, v14, 4
	v_readlane_b32 s25, v14, 5
	v_readlane_b32 s26, v14, 6
	v_readlane_b32 s27, v14, 7
	s_nop 1
	s_add_i32 s55, s14, 8
	s_add_i32 s52, s55, 0
	s_mov_b32 s53, 0
	s_lshl_b64 s[52:53], s[52:53], 14
	s_add_u32 s52, s52, s2
	s_addc_u32 s53, s53, s3
	global_load_dwordx4 v[80:83], v1, s[52:53]
	global_load_dwordx4 v[84:87], v1, s[52:53] offset:1024
	s_add_i32 s52, s55, 1
	s_mov_b32 s53, 0
	s_lshl_b64 s[52:53], s[52:53], 14
	s_add_u32 s52, s52, s2
	s_addc_u32 s53, s53, s3
	global_load_dwordx4 v[88:91], v1, s[52:53]
	global_load_dwordx4 v[92:95], v1, s[52:53] offset:1024
	s_add_i32 s52, s55, 2
	s_mov_b32 s53, 0
	s_lshl_b64 s[52:53], s[52:53], 14
	s_add_u32 s52, s52, s2
	s_addc_u32 s53, s53, s3
	global_load_dwordx4 v[96:99], v1, s[52:53]
	global_load_dwordx4 v[100:103], v1, s[52:53] offset:1024
	s_add_i32 s52, s55, 3
	s_mov_b32 s53, 0
	s_lshl_b64 s[52:53], s[52:53], 14
	s_add_u32 s52, s52, s2
	s_addc_u32 s53, s53, s3
	global_load_dwordx4 v[104:107], v1, s[52:53]
	global_load_dwordx4 v[108:111], v1, s[52:53] offset:1024
	s_add_i32 s52, s55, 4
	s_mov_b32 s53, 0
	s_lshl_b64 s[52:53], s[52:53], 14
	s_add_u32 s52, s52, s2
	s_addc_u32 s53, s53, s3
	global_load_dwordx4 v[112:115], v1, s[52:53]
	global_load_dwordx4 v[116:119], v1, s[52:53] offset:1024
	s_add_i32 s52, s55, 5
	s_mov_b32 s53, 0
	s_lshl_b64 s[52:53], s[52:53], 14
	s_add_u32 s52, s52, s2
	s_addc_u32 s53, s53, s3
	global_load_dwordx4 v[120:123], v1, s[52:53]
	global_load_dwordx4 v[124:127], v1, s[52:53] offset:1024
	s_add_i32 s52, s55, 6
	s_mov_b32 s53, 0
	s_lshl_b64 s[52:53], s[52:53], 14
	s_add_u32 s52, s52, s2
	s_addc_u32 s53, s53, s3
	global_load_dwordx4 v[128:131], v1, s[52:53]
	global_load_dwordx4 v[132:135], v1, s[52:53] offset:1024
	s_add_i32 s52, s55, 7
	s_mov_b32 s53, 0
	s_lshl_b64 s[52:53], s[52:53], 14
	s_add_u32 s52, s52, s2
	s_addc_u32 s53, s53, s3
	global_load_dwordx4 v[136:139], v1, s[52:53]
	global_load_dwordx4 v[140:143], v1, s[52:53] offset:1024
	v_mul_f32_e32 v16, s20, v16
	v_mul_f32_e32 v17, s20, v17
	v_mul_f32_e32 v18, s20, v18
	v_mul_f32_e32 v19, s20, v19
	v_mul_f32_e32 v20, s20, v20
	v_mul_f32_e32 v21, s20, v21
	v_mul_f32_e32 v22, s20, v22
	v_mul_f32_e32 v23, s20, v23
	v_pk_mul_f32 v[16:17], v[16:17], v[4:5]
	v_pk_mul_f32 v[18:19], v[18:19], v[6:7]
	v_pk_mul_f32 v[20:21], v[20:21], v[8:9]
	v_pk_mul_f32 v[22:23], v[22:23], v[10:11]
	v_mul_f32_e32 v24, s21, v24
	v_mul_f32_e32 v25, s21, v25
	v_mul_f32_e32 v26, s21, v26
	v_mul_f32_e32 v27, s21, v27
	v_mul_f32_e32 v28, s21, v28
	v_mul_f32_e32 v29, s21, v29
	v_mul_f32_e32 v30, s21, v30
	v_mul_f32_e32 v31, s21, v31
	v_pk_mul_f32 v[24:25], v[24:25], v[4:5]
	v_pk_mul_f32 v[26:27], v[26:27], v[6:7]
	v_pk_mul_f32 v[28:29], v[28:29], v[8:9]
	v_pk_mul_f32 v[30:31], v[30:31], v[10:11]
	v_mul_f32_e32 v32, s22, v32
	v_mul_f32_e32 v33, s22, v33
	v_mul_f32_e32 v34, s22, v34
	v_mul_f32_e32 v35, s22, v35
	v_mul_f32_e32 v36, s22, v36
	v_mul_f32_e32 v37, s22, v37
	v_mul_f32_e32 v38, s22, v38
	v_mul_f32_e32 v39, s22, v39
	v_pk_mul_f32 v[32:33], v[32:33], v[4:5]
	v_pk_mul_f32 v[34:35], v[34:35], v[6:7]
	v_pk_mul_f32 v[36:37], v[36:37], v[8:9]
	v_pk_mul_f32 v[38:39], v[38:39], v[10:11]
	v_mul_f32_e32 v40, s23, v40
	v_mul_f32_e32 v41, s23, v41
	v_mul_f32_e32 v42, s23, v42
	v_mul_f32_e32 v43, s23, v43
	v_mul_f32_e32 v44, s23, v44
	v_mul_f32_e32 v45, s23, v45
	v_mul_f32_e32 v46, s23, v46
	v_mul_f32_e32 v47, s23, v47
	v_pk_mul_f32 v[40:41], v[40:41], v[4:5]
	v_pk_mul_f32 v[42:43], v[42:43], v[6:7]
	v_pk_mul_f32 v[44:45], v[44:45], v[8:9]
	v_pk_mul_f32 v[46:47], v[46:47], v[10:11]
	v_mul_f32_e32 v48, s24, v48
	v_mul_f32_e32 v49, s24, v49
	v_mul_f32_e32 v50, s24, v50
	v_mul_f32_e32 v51, s24, v51
	v_mul_f32_e32 v52, s24, v52
	v_mul_f32_e32 v53, s24, v53
	v_mul_f32_e32 v54, s24, v54
	v_mul_f32_e32 v55, s24, v55
	v_pk_mul_f32 v[48:49], v[48:49], v[4:5]
	v_pk_mul_f32 v[50:51], v[50:51], v[6:7]
	v_pk_mul_f32 v[52:53], v[52:53], v[8:9]
	v_pk_mul_f32 v[54:55], v[54:55], v[10:11]
	v_mul_f32_e32 v56, s25, v56
	v_mul_f32_e32 v57, s25, v57
	v_mul_f32_e32 v58, s25, v58
	v_mul_f32_e32 v59, s25, v59
	v_mul_f32_e32 v60, s25, v60
	v_mul_f32_e32 v61, s25, v61
	v_mul_f32_e32 v62, s25, v62
	v_mul_f32_e32 v63, s25, v63
	v_pk_mul_f32 v[56:57], v[56:57], v[4:5]
	v_pk_mul_f32 v[58:59], v[58:59], v[6:7]
	v_pk_mul_f32 v[60:61], v[60:61], v[8:9]
	v_pk_mul_f32 v[62:63], v[62:63], v[10:11]
	v_mul_f32_e32 v64, s26, v64
	v_mul_f32_e32 v65, s26, v65
	v_mul_f32_e32 v66, s26, v66
	v_mul_f32_e32 v67, s26, v67
	v_mul_f32_e32 v68, s26, v68
	v_mul_f32_e32 v69, s26, v69
	v_mul_f32_e32 v70, s26, v70
	v_mul_f32_e32 v71, s26, v71
	v_pk_mul_f32 v[64:65], v[64:65], v[4:5]
	v_pk_mul_f32 v[66:67], v[66:67], v[6:7]
	v_pk_mul_f32 v[68:69], v[68:69], v[8:9]
	v_pk_mul_f32 v[70:71], v[70:71], v[10:11]
	v_mul_f32_e32 v72, s27, v72
	v_mul_f32_e32 v73, s27, v73
	v_mul_f32_e32 v74, s27, v74
	v_mul_f32_e32 v75, s27, v75
	v_mul_f32_e32 v76, s27, v76
	v_mul_f32_e32 v77, s27, v77
	v_mul_f32_e32 v78, s27, v78
	v_mul_f32_e32 v79, s27, v79
	v_pk_mul_f32 v[72:73], v[72:73], v[4:5]
	v_pk_mul_f32 v[74:75], v[74:75], v[6:7]
	v_pk_mul_f32 v[76:77], v[76:77], v[8:9]
	v_pk_mul_f32 v[78:79], v[78:79], v[10:11]
	v_pk_add_f32 v[208:209], v[208:209], v[16:17]
	v_pk_add_f32 v[210:211], v[210:211], v[18:19]
	v_pk_add_f32 v[212:213], v[212:213], v[20:21]
	v_pk_add_f32 v[214:215], v[214:215], v[22:23]
	v_pk_add_f32 v[208:209], v[208:209], v[24:25]
	v_pk_add_f32 v[210:211], v[210:211], v[26:27]
	v_pk_add_f32 v[212:213], v[212:213], v[28:29]
	v_pk_add_f32 v[214:215], v[214:215], v[30:31]
	v_pk_add_f32 v[208:209], v[208:209], v[32:33]
	v_pk_add_f32 v[210:211], v[210:211], v[34:35]
	v_pk_add_f32 v[212:213], v[212:213], v[36:37]
	v_pk_add_f32 v[214:215], v[214:215], v[38:39]
	v_pk_add_f32 v[208:209], v[208:209], v[40:41]
	v_pk_add_f32 v[210:211], v[210:211], v[42:43]
	v_pk_add_f32 v[212:213], v[212:213], v[44:45]
	v_pk_add_f32 v[214:215], v[214:215], v[46:47]
	v_pk_add_f32 v[208:209], v[208:209], v[48:49]
	v_pk_add_f32 v[210:211], v[210:211], v[50:51]
	v_pk_add_f32 v[212:213], v[212:213], v[52:53]
	v_pk_add_f32 v[214:215], v[214:215], v[54:55]
	v_pk_add_f32 v[208:209], v[208:209], v[56:57]
	v_pk_add_f32 v[210:211], v[210:211], v[58:59]
	v_pk_add_f32 v[212:213], v[212:213], v[60:61]
	v_pk_add_f32 v[214:215], v[214:215], v[62:63]
	v_pk_add_f32 v[208:209], v[208:209], v[64:65]
	v_pk_add_f32 v[210:211], v[210:211], v[66:67]
	v_pk_add_f32 v[212:213], v[212:213], v[68:69]
	v_pk_add_f32 v[214:215], v[214:215], v[70:71]
	v_pk_add_f32 v[208:209], v[208:209], v[72:73]
	v_pk_add_f32 v[210:211], v[210:211], v[74:75]
	v_pk_add_f32 v[212:213], v[212:213], v[76:77]
	v_pk_add_f32 v[214:215], v[214:215], v[78:79]
	s_add_i32 s13, s13, 1
	s_add_i32 s14, s14, 8
	s_add_i32 s15, s15, 8
	s_waitcnt vmcnt(0)
	v_mul_f32_e32 v16, v80, v80
	v_fmac_f32_e32 v16, v81, v81
	v_fmac_f32_e32 v16, v82, v82
	v_fmac_f32_e32 v16, v83, v83
	v_fmac_f32_e32 v16, v84, v84
	v_fmac_f32_e32 v16, v85, v85
	v_fmac_f32_e32 v16, v86, v86
	v_fmac_f32_e32 v16, v87, v87
	v_mul_f32_e32 v17, v88, v88
	v_fmac_f32_e32 v17, v89, v89
	v_fmac_f32_e32 v17, v90, v90
	v_fmac_f32_e32 v17, v91, v91
	v_fmac_f32_e32 v17, v92, v92
	v_fmac_f32_e32 v17, v93, v93
	v_fmac_f32_e32 v17, v94, v94
	v_fmac_f32_e32 v17, v95, v95
	v_mul_f32_e32 v18, v96, v96
	v_fmac_f32_e32 v18, v97, v97
	v_fmac_f32_e32 v18, v98, v98
	v_fmac_f32_e32 v18, v99, v99
	v_fmac_f32_e32 v18, v100, v100
	v_fmac_f32_e32 v18, v101, v101
	v_fmac_f32_e32 v18, v102, v102
	v_fmac_f32_e32 v18, v103, v103
	v_mul_f32_e32 v19, v104, v104
	v_fmac_f32_e32 v19, v105, v105
	v_fmac_f32_e32 v19, v106, v106
	v_fmac_f32_e32 v19, v107, v107
	v_fmac_f32_e32 v19, v108, v108
	v_fmac_f32_e32 v19, v109, v109
	v_fmac_f32_e32 v19, v110, v110
	v_fmac_f32_e32 v19, v111, v111
	v_mul_f32_e32 v20, v112, v112
	v_fmac_f32_e32 v20, v113, v113
	v_fmac_f32_e32 v20, v114, v114
	v_fmac_f32_e32 v20, v115, v115
	v_fmac_f32_e32 v20, v116, v116
	v_fmac_f32_e32 v20, v117, v117
	v_fmac_f32_e32 v20, v118, v118
	v_fmac_f32_e32 v20, v119, v119
	v_mul_f32_e32 v21, v120, v120
	v_fmac_f32_e32 v21, v121, v121
	v_fmac_f32_e32 v21, v122, v122
	v_fmac_f32_e32 v21, v123, v123
	v_fmac_f32_e32 v21, v124, v124
	v_fmac_f32_e32 v21, v125, v125
	v_fmac_f32_e32 v21, v126, v126
	v_fmac_f32_e32 v21, v127, v127
	v_mul_f32_e32 v22, v128, v128
	v_fmac_f32_e32 v22, v129, v129
	v_fmac_f32_e32 v22, v130, v130
	v_fmac_f32_e32 v22, v131, v131
	v_fmac_f32_e32 v22, v132, v132
	v_fmac_f32_e32 v22, v133, v133
	v_fmac_f32_e32 v22, v134, v134
	v_fmac_f32_e32 v22, v135, v135
	v_mul_f32_e32 v23, v136, v136
	v_fmac_f32_e32 v23, v137, v137
	v_fmac_f32_e32 v23, v138, v138
	v_fmac_f32_e32 v23, v139, v139
	v_fmac_f32_e32 v23, v140, v140
	v_fmac_f32_e32 v23, v141, v141
	v_fmac_f32_e32 v23, v142, v142
	v_fmac_f32_e32 v23, v143, v143
	s_nop 1
	v_add_f32_dpp v16, v16, v16 quad_perm:[1,0,3,2] row_mask:0xf bank_mask:0xf bound_ctrl:1
	v_add_f32_dpp v17, v17, v17 quad_perm:[1,0,3,2] row_mask:0xf bank_mask:0xf bound_ctrl:1
	v_add_f32_dpp v18, v18, v18 quad_perm:[1,0,3,2] row_mask:0xf bank_mask:0xf bound_ctrl:1
	v_add_f32_dpp v19, v19, v19 quad_perm:[1,0,3,2] row_mask:0xf bank_mask:0xf bound_ctrl:1
	v_add_f32_dpp v20, v20, v20 quad_perm:[1,0,3,2] row_mask:0xf bank_mask:0xf bound_ctrl:1
	v_add_f32_dpp v21, v21, v21 quad_perm:[1,0,3,2] row_mask:0xf bank_mask:0xf bound_ctrl:1
	v_add_f32_dpp v22, v22, v22 quad_perm:[1,0,3,2] row_mask:0xf bank_mask:0xf bound_ctrl:1
	v_add_f32_dpp v23, v23, v23 quad_perm:[1,0,3,2] row_mask:0xf bank_mask:0xf bound_ctrl:1
	s_nop 1
	v_add_f32_dpp v16, v16, v16 quad_perm:[2,3,0,1] row_mask:0xf bank_mask:0xf bound_ctrl:1
	v_add_f32_dpp v17, v17, v17 quad_perm:[2,3,0,1] row_mask:0xf bank_mask:0xf bound_ctrl:1
	v_add_f32_dpp v18, v18, v18 quad_perm:[2,3,0,1] row_mask:0xf bank_mask:0xf bound_ctrl:1
	v_add_f32_dpp v19, v19, v19 quad_perm:[2,3,0,1] row_mask:0xf bank_mask:0xf bound_ctrl:1
	v_add_f32_dpp v20, v20, v20 quad_perm:[2,3,0,1] row_mask:0xf bank_mask:0xf bound_ctrl:1
	v_add_f32_dpp v21, v21, v21 quad_perm:[2,3,0,1] row_mask:0xf bank_mask:0xf bound_ctrl:1
	v_add_f32_dpp v22, v22, v22 quad_perm:[2,3,0,1] row_mask:0xf bank_mask:0xf bound_ctrl:1
	v_add_f32_dpp v23, v23, v23 quad_perm:[2,3,0,1] row_mask:0xf bank_mask:0xf bound_ctrl:1
	s_nop 1
	v_add_f32_dpp v16, v16, v16 row_half_mirror row_mask:0xf bank_mask:0xf bound_ctrl:1
	v_add_f32_dpp v17, v17, v17 row_half_mirror row_mask:0xf bank_mask:0xf bound_ctrl:1
	v_add_f32_dpp v18, v18, v18 row_half_mirror row_mask:0xf bank_mask:0xf bound_ctrl:1
	v_add_f32_dpp v19, v19, v19 row_half_mirror row_mask:0xf bank_mask:0xf bound_ctrl:1
	v_add_f32_dpp v20, v20, v20 row_half_mirror row_mask:0xf bank_mask:0xf bound_ctrl:1
	v_add_f32_dpp v21, v21, v21 row_half_mirror row_mask:0xf bank_mask:0xf bound_ctrl:1
	v_add_f32_dpp v22, v22, v22 row_half_mirror row_mask:0xf bank_mask:0xf bound_ctrl:1
	v_add_f32_dpp v23, v23, v23 row_half_mirror row_mask:0xf bank_mask:0xf bound_ctrl:1
	s_nop 1
	v_add_f32_dpp v16, v16, v16 row_mirror row_mask:0xf bank_mask:0xf bound_ctrl:1
	v_add_f32_dpp v17, v17, v17 row_mirror row_mask:0xf bank_mask:0xf bound_ctrl:1
	v_add_f32_dpp v18, v18, v18 row_mirror row_mask:0xf bank_mask:0xf bound_ctrl:1
	v_add_f32_dpp v19, v19, v19 row_mirror row_mask:0xf bank_mask:0xf bound_ctrl:1
	v_add_f32_dpp v20, v20, v20 row_mirror row_mask:0xf bank_mask:0xf bound_ctrl:1
	v_add_f32_dpp v21, v21, v21 row_mirror row_mask:0xf bank_mask:0xf bound_ctrl:1
	v_add_f32_dpp v22, v22, v22 row_mirror row_mask:0xf bank_mask:0xf bound_ctrl:1
	v_add_f32_dpp v23, v23, v23 row_mirror row_mask:0xf bank_mask:0xf bound_ctrl:1
	v_lshrrev_b32_e32 v12, 6, v1
	v_and_b32_e32 v12, 12, v12
	s_lshl_b32 s52, s9, 4
	s_add_i32 s52, s52, 1024
	v_add_u32_e32 v12, s52, v12
	s_mov_b32 exec_lo, 0x10001
	s_mov_b32 exec_hi, 0x10001
	ds_write_b32 v12, v16
	ds_write_b32 v12, v17 offset:128
	ds_write_b32 v12, v18 offset:256
	ds_write_b32 v12, v19 offset:384
	ds_write_b32 v12, v20 offset:512
	ds_write_b32 v12, v21 offset:640
	ds_write_b32 v12, v22 offset:768
	ds_write_b32 v12, v23 offset:896
	s_mov_b64 exec, -1
	s_waitcnt lgkmcnt(0)
	s_barrier
	v_lshrrev_b32_e32 v13, 4, v1
	v_and_b32_e32 v13, 7, v13
	v_lshlrev_b32_e32 v12, 7, v13
	v_add_u32_e32 v12, 0x400, v12
	ds_read_b128 v[24:27], v12
	ds_read_b128 v[28:31], v12 offset:16
	ds_read_b128 v[32:35], v12 offset:32
	ds_read_b128 v[36:39], v12 offset:48
	ds_read_b128 v[40:43], v12 offset:64
	ds_read_b128 v[44:47], v12 offset:80
	ds_read_b128 v[48:51], v12 offset:96
	ds_read_b128 v[52:55], v12 offset:112
	s_waitcnt lgkmcnt(0)
	v_add_f32_e32 v14, v24, v25
	v_add_f32_e32 v14, v14, v26
	v_add_f32_e32 v14, v14, v27
	v_add_f32_e32 v14, v14, v28
	v_add_f32_e32 v14, v14, v29
	v_add_f32_e32 v14, v14, v30
	v_add_f32_e32 v14, v14, v31
	v_add_f32_e32 v14, v14, v32
	v_add_f32_e32 v14, v14, v33
	v_add_f32_e32 v14, v14, v34
	v_add_f32_e32 v14, v14, v35
	v_add_f32_e32 v14, v14, v36
	v_add_f32_e32 v14, v14, v37
	v_add_f32_e32 v14, v14, v38
	v_add_f32_e32 v14, v14, v39
	v_add_f32_e32 v14, v14, v40
	v_add_f32_e32 v14, v14, v41
	v_add_f32_e32 v14, v14, v42
	v_add_f32_e32 v14, v14, v43
	v_add_f32_e32 v14, v14, v44
	v_add_f32_e32 v14, v14, v45
	v_add_f32_e32 v14, v14, v46
	v_add_f32_e32 v14, v14, v47
	v_add_f32_e32 v14, v14, v48
	v_add_f32_e32 v14, v14, v49
	v_add_f32_e32 v14, v14, v50
	v_add_f32_e32 v14, v14, v51
	v_add_f32_e32 v14, v14, v52
	v_add_f32_e32 v14, v14, v53
	v_add_f32_e32 v14, v14, v54
	v_add_f32_e32 v14, v14, v55
	v_mov_b32_e32 v221, 0x358637bd
	v_mov_b32_e32 v222, 0x260
	s_mov_b32 s54, 0xf800000
	v_fmamk_f32 v14, v14, 0x39800000, v221
	v_mul_f32_e32 v15, 0x4f800000, v14
	v_cmp_gt_f32_e32 vcc, s54, v14
	s_nop 1
	v_cndmask_b32_e32 v14, v14, v15, vcc
	v_sqrt_f32_e32 v15, v14
	s_nop 0
	v_add_u32_e32 v216, -1, v15
	v_add_u32_e32 v217, 1, v15
	v_fma_f32 v218, -v216, v15, v14
	v_fma_f32 v220, -v217, v15, v14
	v_cmp_ge_f32_e64 s[30:31], 0, v218
	s_nop 1
	v_cndmask_b32_e64 v15, v15, v216, s[30:31]
	v_cmp_lt_f32_e64 s[30:31], 0, v220
	s_nop 1
	v_cndmask_b32_e64 v15, v15, v217, s[30:31]
	v_mul_f32_e32 v216, 0x37800000, v15
	v_cndmask_b32_e32 v15, v15, v216, vcc
	v_cmp_class_f32_e32 vcc, v14, v222
	s_nop 1
	v_cndmask_b32_e32 v14, v15, v14, vcc
	v_div_scale_f32 v15, s[30:31], v14, v14, 1.0
	v_rcp_f32_e32 v216, v15
	v_div_scale_f32 v217, vcc, 1.0, v14, 1.0
	v_fma_f32 v218, -v15, v216, 1.0
	v_fmac_f32_e32 v216, v218, v216
	v_mul_f32_e32 v218, v217, v216
	v_fma_f32 v220, -v15, v218, v217
	v_fmac_f32_e32 v218, v220, v216
	v_fma_f32 v15, -v15, v218, v217
	v_div_fmas_f32 v15, v15, v216, v218
	v_div_fixup_f32 v14, v15, v14, 1.0
	s_mul_i32 s52, s9, 320
	s_lshl_b32 s53, s13, 5
	s_add_i32 s52, s52, s53
	s_add_i32 s52, s52, 0x800
	v_lshl_add_u32 v12, v13, 2, s52
	ds_write_b32 v12, v14
	s_lshl_b32 s53, s13, 3
	s_sub_i32 s53, 16, s53
	v_sub_u32_e32 v15, s53, v13
	v_cmp_ge_u32_e32 vcc, s12, v15
	s_nop 1
	v_cndmask_b32_e32 v14, 0, v14, vcc
	s_nop 1
	v_readlane_b32 s20, v14, 0
	v_readlane_b32 s21, v14, 1
	v_readlane_b32 s22, v14, 2
	v_readlane_b32 s23, v14, 3
	v_readlane_b32 s24, v14, 4
	v_readlane_b32 s25, v14, 5
	v_readlane_b32 s26, v14, 6
	v_readlane_b32 s27, v14, 7
	s_nop 1
	s_add_i32 s55, s14, 8
	s_add_i32 s52, s55, 0
	s_mov_b32 s53, 0
	s_lshl_b64 s[52:53], s[52:53], 14
	s_add_u32 s52, s52, s2
	s_addc_u32 s53, s53, s3
	global_load_dwordx4 v[16:19], v1, s[52:53]
	global_load_dwordx4 v[20:23], v1, s[52:53] offset:1024
	s_add_i32 s52, s55, 1
	s_mov_b32 s53, 0
	s_lshl_b64 s[52:53], s[52:53], 14
	s_add_u32 s52, s52, s2
	s_addc_u32 s53, s53, s3
	global_load_dwordx4 v[24:27], v1, s[52:53]
	global_load_dwordx4 v[28:31], v1, s[52:53] offset:1024
	s_add_i32 s52, s55, 2
	s_mov_b32 s53, 0
	s_lshl_b64 s[52:53], s[52:53], 14
	s_add_u32 s52, s52, s2
	s_addc_u32 s53, s53, s3
	global_load_dwordx4 v[32:35], v1, s[52:53]
	global_load_dwordx4 v[36:39], v1, s[52:53] offset:1024
	s_add_i32 s52, s55, 3
	s_mov_b32 s53, 0
	s_lshl_b64 s[52:53], s[52:53], 14
	s_add_u32 s52, s52, s2
	s_addc_u32 s53, s53, s3
	global_load_dwordx4 v[40:43], v1, s[52:53]
	global_load_dwordx4 v[44:47], v1, s[52:53] offset:1024
	s_add_i32 s52, s55, 4
	s_mov_b32 s53, 0
	s_lshl_b64 s[52:53], s[52:53], 14
	s_add_u32 s52, s52, s2
	s_addc_u32 s53, s53, s3
	global_load_dwordx4 v[48:51], v1, s[52:53]
	global_load_dwordx4 v[52:55], v1, s[52:53] offset:1024
	s_add_i32 s52, s55, 5
	s_mov_b32 s53, 0
	s_lshl_b64 s[52:53], s[52:53], 14
	s_add_u32 s52, s52, s2
	s_addc_u32 s53, s53, s3
	global_load_dwordx4 v[56:59], v1, s[52:53]
	global_load_dwordx4 v[60:63], v1, s[52:53] offset:1024
	s_add_i32 s52, s55, 6
	s_mov_b32 s53, 0
	s_lshl_b64 s[52:53], s[52:53], 14
	s_add_u32 s52, s52, s2
	s_addc_u32 s53, s53, s3
	global_load_dwordx4 v[64:67], v1, s[52:53]
	global_load_dwordx4 v[68:71], v1, s[52:53] offset:1024
	s_add_i32 s52, s55, 7
	s_mov_b32 s53, 0
	s_lshl_b64 s[52:53], s[52:53], 14
	s_add_u32 s52, s52, s2
	s_addc_u32 s53, s53, s3
	global_load_dwordx4 v[72:75], v1, s[52:53]
	global_load_dwordx4 v[76:79], v1, s[52:53] offset:1024
	v_mul_f32_e32 v80, s20, v80
	v_mul_f32_e32 v81, s20, v81
	v_mul_f32_e32 v82, s20, v82
	v_mul_f32_e32 v83, s20, v83
	v_mul_f32_e32 v84, s20, v84
	v_mul_f32_e32 v85, s20, v85
	v_mul_f32_e32 v86, s20, v86
	v_mul_f32_e32 v87, s20, v87
	v_pk_mul_f32 v[80:81], v[80:81], v[4:5]
	v_pk_mul_f32 v[82:83], v[82:83], v[6:7]
	v_pk_mul_f32 v[84:85], v[84:85], v[8:9]
	v_pk_mul_f32 v[86:87], v[86:87], v[10:11]
	v_mul_f32_e32 v88, s21, v88
	v_mul_f32_e32 v89, s21, v89
	v_mul_f32_e32 v90, s21, v90
	v_mul_f32_e32 v91, s21, v91
	v_mul_f32_e32 v92, s21, v92
	v_mul_f32_e32 v93, s21, v93
	v_mul_f32_e32 v94, s21, v94
	v_mul_f32_e32 v95, s21, v95
	v_pk_mul_f32 v[88:89], v[88:89], v[4:5]
	v_pk_mul_f32 v[90:91], v[90:91], v[6:7]
	v_pk_mul_f32 v[92:93], v[92:93], v[8:9]
	v_pk_mul_f32 v[94:95], v[94:95], v[10:11]
	v_mul_f32_e32 v96, s22, v96
	v_mul_f32_e32 v97, s22, v97
	v_mul_f32_e32 v98, s22, v98
	v_mul_f32_e32 v99, s22, v99
	v_mul_f32_e32 v100, s22, v100
	v_mul_f32_e32 v101, s22, v101
	v_mul_f32_e32 v102, s22, v102
	v_mul_f32_e32 v103, s22, v103
	v_pk_mul_f32 v[96:97], v[96:97], v[4:5]
	v_pk_mul_f32 v[98:99], v[98:99], v[6:7]
	v_pk_mul_f32 v[100:101], v[100:101], v[8:9]
	v_pk_mul_f32 v[102:103], v[102:103], v[10:11]
	v_mul_f32_e32 v104, s23, v104
	v_mul_f32_e32 v105, s23, v105
	v_mul_f32_e32 v106, s23, v106
	v_mul_f32_e32 v107, s23, v107
	v_mul_f32_e32 v108, s23, v108
	v_mul_f32_e32 v109, s23, v109
	v_mul_f32_e32 v110, s23, v110
	v_mul_f32_e32 v111, s23, v111
	v_pk_mul_f32 v[104:105], v[104:105], v[4:5]
	v_pk_mul_f32 v[106:107], v[106:107], v[6:7]
	v_pk_mul_f32 v[108:109], v[108:109], v[8:9]
	v_pk_mul_f32 v[110:111], v[110:111], v[10:11]
	v_mul_f32_e32 v112, s24, v112
	v_mul_f32_e32 v113, s24, v113
	v_mul_f32_e32 v114, s24, v114
	v_mul_f32_e32 v115, s24, v115
	v_mul_f32_e32 v116, s24, v116
	v_mul_f32_e32 v117, s24, v117
	v_mul_f32_e32 v118, s24, v118
	v_mul_f32_e32 v119, s24, v119
	v_pk_mul_f32 v[112:113], v[112:113], v[4:5]
	v_pk_mul_f32 v[114:115], v[114:115], v[6:7]
	v_pk_mul_f32 v[116:117], v[116:117], v[8:9]
	v_pk_mul_f32 v[118:119], v[118:119], v[10:11]
	v_mul_f32_e32 v120, s25, v120
	v_mul_f32_e32 v121, s25, v121
	v_mul_f32_e32 v122, s25, v122
	v_mul_f32_e32 v123, s25, v123
	v_mul_f32_e32 v124, s25, v124
	v_mul_f32_e32 v125, s25, v125
	v_mul_f32_e32 v126, s25, v126
	v_mul_f32_e32 v127, s25, v127
	v_pk_mul_f32 v[120:121], v[120:121], v[4:5]
	v_pk_mul_f32 v[122:123], v[122:123], v[6:7]
	v_pk_mul_f32 v[124:125], v[124:125], v[8:9]
	v_pk_mul_f32 v[126:127], v[126:127], v[10:11]
	v_mul_f32_e32 v128, s26, v128
	v_mul_f32_e32 v129, s26, v129
	v_mul_f32_e32 v130, s26, v130
	v_mul_f32_e32 v131, s26, v131
	v_mul_f32_e32 v132, s26, v132
	v_mul_f32_e32 v133, s26, v133
	v_mul_f32_e32 v134, s26, v134
	v_mul_f32_e32 v135, s26, v135
	v_pk_mul_f32 v[128:129], v[128:129], v[4:5]
	v_pk_mul_f32 v[130:131], v[130:131], v[6:7]
	v_pk_mul_f32 v[132:133], v[132:133], v[8:9]
	v_pk_mul_f32 v[134:135], v[134:135], v[10:11]
	v_mul_f32_e32 v136, s27, v136
	v_mul_f32_e32 v137, s27, v137
	v_mul_f32_e32 v138, s27, v138
	v_mul_f32_e32 v139, s27, v139
	v_mul_f32_e32 v140, s27, v140
	v_mul_f32_e32 v141, s27, v141
	v_mul_f32_e32 v142, s27, v142
	v_mul_f32_e32 v143, s27, v143
	v_pk_mul_f32 v[136:137], v[136:137], v[4:5]
	v_pk_mul_f32 v[138:139], v[138:139], v[6:7]
	v_pk_mul_f32 v[140:141], v[140:141], v[8:9]
	v_pk_mul_f32 v[142:143], v[142:143], v[10:11]
	v_pk_add_f32 v[208:209], v[208:209], v[80:81]
	v_pk_add_f32 v[210:211], v[210:211], v[82:83]
	v_pk_add_f32 v[212:213], v[212:213], v[84:85]
	v_pk_add_f32 v[214:215], v[214:215], v[86:87]
	v_pk_add_f32 v[208:209], v[208:209], v[88:89]
	v_pk_add_f32 v[210:211], v[210:211], v[90:91]
	v_pk_add_f32 v[212:213], v[212:213], v[92:93]
	v_pk_add_f32 v[214:215], v[214:215], v[94:95]
	v_pk_add_f32 v[208:209], v[208:209], v[96:97]
	v_pk_add_f32 v[210:211], v[210:211], v[98:99]
	v_pk_add_f32 v[212:213], v[212:213], v[100:101]
	v_pk_add_f32 v[214:215], v[214:215], v[102:103]
	v_pk_add_f32 v[208:209], v[208:209], v[104:105]
	v_pk_add_f32 v[210:211], v[210:211], v[106:107]
	v_pk_add_f32 v[212:213], v[212:213], v[108:109]
	v_pk_add_f32 v[214:215], v[214:215], v[110:111]
	v_pk_add_f32 v[208:209], v[208:209], v[112:113]
	v_pk_add_f32 v[210:211], v[210:211], v[114:115]
	v_pk_add_f32 v[212:213], v[212:213], v[116:117]
	v_pk_add_f32 v[214:215], v[214:215], v[118:119]
	v_pk_add_f32 v[208:209], v[208:209], v[120:121]
	v_pk_add_f32 v[210:211], v[210:211], v[122:123]
	v_pk_add_f32 v[212:213], v[212:213], v[124:125]
	v_pk_add_f32 v[214:215], v[214:215], v[126:127]
	v_pk_add_f32 v[208:209], v[208:209], v[128:129]
	v_pk_add_f32 v[210:211], v[210:211], v[130:131]
	v_pk_add_f32 v[212:213], v[212:213], v[132:133]
	v_pk_add_f32 v[214:215], v[214:215], v[134:135]
	v_pk_add_f32 v[208:209], v[208:209], v[136:137]
	v_pk_add_f32 v[210:211], v[210:211], v[138:139]
	v_pk_add_f32 v[212:213], v[212:213], v[140:141]
	v_pk_add_f32 v[214:215], v[214:215], v[142:143]
	s_add_i32 s13, s13, 1
	s_add_i32 s14, s14, 8
	s_add_i32 s15, s15, 8
	s_branch .Lp1f_main
.Lp1f_nohalo:
	s_mov_b32 s13, 2
	s_mov_b32 s14, s10
	s_mov_b32 s15, s11
	s_add_i32 s52, s14, 0
	s_mov_b32 s53, 0
	s_lshl_b64 s[52:53], s[52:53], 14
	s_add_u32 s52, s52, s2
	s_addc_u32 s53, s53, s3
	global_load_dwordx4 v[16:19], v1, s[52:53]
	global_load_dwordx4 v[20:23], v1, s[52:53] offset:1024
	s_add_i32 s52, s14, 1
	s_mov_b32 s53, 0
	s_lshl_b64 s[52:53], s[52:53], 14
	s_add_u32 s52, s52, s2
	s_addc_u32 s53, s53, s3
	global_load_dwordx4 v[24:27], v1, s[52:53]
	global_load_dwordx4 v[28:31], v1, s[52:53] offset:1024
	s_add_i32 s52, s14, 2
	s_mov_b32 s53, 0
	s_lshl_b64 s[52:53], s[52:53], 14
	s_add_u32 s52, s52, s2
	s_addc_u32 s53, s53, s3
	global_load_dwordx4 v[32:35], v1, s[52:53]
	global_load_dwordx4 v[36:39], v1, s[52:53] offset:1024
	s_add_i32 s52, s14, 3
	s_mov_b32 s53, 0
	s_lshl_b64 s[52:53], s[52:53], 14
	s_add_u32 s52, s52, s2
	s_addc_u32 s53, s53, s3
	global_load_dwordx4 v[40:43], v1, s[52:53]
	global_load_dwordx4 v[44:47], v1, s[52:53] offset:1024
	s_add_i32 s52, s14, 4
	s_mov_b32 s53, 0
	s_lshl_b64 s[52:53], s[52:53], 14
	s_add_u32 s52, s52, s2
	s_addc_u32 s53, s53, s3
	global_load_dwordx4 v[48:51], v1, s[52:53]
	global_load_dwordx4 v[52:55], v1, s[52:53] offset:1024
	s_add_i32 s52, s14, 5
	s_mov_b32 s53, 0
	s_lshl_b64 s[52:53], s[52:53], 14
	s_add_u32 s52, s52, s2
	s_addc_u32 s53, s53, s3
	global_load_dwordx4 v[56:59], v1, s[52:53]
	global_load_dwordx4 v[60:63], v1, s[52:53] offset:1024
	s_add_i32 s52, s14, 6
	s_mov_b32 s53, 0
	s_lshl_b64 s[52:53], s[52:53], 14
	s_add_u32 s52, s52, s2
	s_addc_u32 s53, s53, s3
	global_load_dwordx4 v[64:67], v1, s[52:53]
	global_load_dwordx4 v[68:71], v1, s[52:53] offset:1024
	s_add_i32 s52, s14, 7
	s_mov_b32 s53, 0
	s_lshl_b64 s[52:53], s[52:53], 14
	s_add_u32 s52, s52, s2
	s_addc_u32 s53, s53, s3
	global_load_dwordx4 v[72:75], v1, s[52:53]
	global_load_dwordx4 v[76:79], v1, s[52:53] offset:1024

.Lp1f_loop:
	s_waitcnt vmcnt(16)
	v_mul_f32_e32 v80, v16, v16
	v_fmac_f32_e32 v80, v17, v17
	v_fmac_f32_e32 v80, v18, v18
	v_fmac_f32_e32 v80, v19, v19
	v_fmac_f32_e32 v80, v20, v20
	v_fmac_f32_e32 v80, v21, v21
	v_fmac_f32_e32 v80, v22, v22
	v_fmac_f32_e32 v80, v23, v23
	v_mul_f32_e32 v81, v24, v24
	v_fmac_f32_e32 v81, v25, v25
	v_fmac_f32_e32 v81, v26, v26
	v_fmac_f32_e32 v81, v27, v27
	v_fmac_f32_e32 v81, v28, v28
	v_fmac_f32_e32 v81, v29, v29
	v_fmac_f32_e32 v81, v30, v30
	v_fmac_f32_e32 v81, v31, v31
	v_mul_f32_e32 v82, v32, v32
	v_fmac_f32_e32 v82, v33, v33
	v_fmac_f32_e32 v82, v34, v34
	v_fmac_f32_e32 v82, v35, v35
	v_fmac_f32_e32 v82, v36, v36
	v_fmac_f32_e32 v82, v37, v37
	v_fmac_f32_e32 v82, v38, v38
	v_fmac_f32_e32 v82, v39, v39
	v_mul_f32_e32 v83, v40, v40
	v_fmac_f32_e32 v83, v41, v41
	v_fmac_f32_e32 v83, v42, v42
	v_fmac_f32_e32 v83, v43, v43
	v_fmac_f32_e32 v83, v44, v44
	v_fmac_f32_e32 v83, v45, v45
	v_fmac_f32_e32 v83, v46, v46
	v_fmac_f32_e32 v83, v47, v47
	v_mul_f32_e32 v84, v48, v48
	v_fmac_f32_e32 v84, v49, v49
	v_fmac_f32_e32 v84, v50, v50
	v_fmac_f32_e32 v84, v51, v51
	v_fmac_f32_e32 v84, v52, v52
	v_fmac_f32_e32 v84, v53, v53
	v_fmac_f32_e32 v84, v54, v54
	v_fmac_f32_e32 v84, v55, v55
	v_mul_f32_e32 v85, v56, v56
	v_fmac_f32_e32 v85, v57, v57
	v_fmac_f32_e32 v85, v58, v58
	v_fmac_f32_e32 v85, v59, v59
	v_fmac_f32_e32 v85, v60, v60
	v_fmac_f32_e32 v85, v61, v61
	v_fmac_f32_e32 v85, v62, v62
	v_fmac_f32_e32 v85, v63, v63
	v_mul_f32_e32 v86, v64, v64
	v_fmac_f32_e32 v86, v65, v65
	v_fmac_f32_e32 v86, v66, v66
	v_fmac_f32_e32 v86, v67, v67
	v_fmac_f32_e32 v86, v68, v68
	v_fmac_f32_e32 v86, v69, v69
	v_fmac_f32_e32 v86, v70, v70
	v_fmac_f32_e32 v86, v71, v71
	v_mul_f32_e32 v87, v72, v72
	v_fmac_f32_e32 v87, v73, v73
	v_fmac_f32_e32 v87, v74, v74
	v_fmac_f32_e32 v87, v75, v75
	v_fmac_f32_e32 v87, v76, v76
	v_fmac_f32_e32 v87, v77, v77
	v_fmac_f32_e32 v87, v78, v78
	v_fmac_f32_e32 v87, v79, v79
	s_nop 1
	v_add_f32_dpp v80, v80, v80 quad_perm:[1,0,3,2] row_mask:0xf bank_mask:0xf bound_ctrl:1
	v_add_f32_dpp v81, v81, v81 quad_perm:[1,0,3,2] row_mask:0xf bank_mask:0xf bound_ctrl:1
	v_add_f32_dpp v82, v82, v82 quad_perm:[1,0,3,2] row_mask:0xf bank_mask:0xf bound_ctrl:1
	v_add_f32_dpp v83, v83, v83 quad_perm:[1,0,3,2] row_mask:0xf bank_mask:0xf bound_ctrl:1
	v_add_f32_dpp v84, v84, v84 quad_perm:[1,0,3,2] row_mask:0xf bank_mask:0xf bound_ctrl:1
	v_add_f32_dpp v85, v85, v85 quad_perm:[1,0,3,2] row_mask:0xf bank_mask:0xf bound_ctrl:1
	v_add_f32_dpp v86, v86, v86 quad_perm:[1,0,3,2] row_mask:0xf bank_mask:0xf bound_ctrl:1
	v_add_f32_dpp v87, v87, v87 quad_perm:[1,0,3,2] row_mask:0xf bank_mask:0xf bound_ctrl:1
	s_nop 1
	v_add_f32_dpp v80, v80, v80 quad_perm:[2,3,0,1] row_mask:0xf bank_mask:0xf bound_ctrl:1
	v_add_f32_dpp v81, v81, v81 quad_perm:[2,3,0,1] row_mask:0xf bank_mask:0xf bound_ctrl:1
	v_add_f32_dpp v82, v82, v82 quad_perm:[2,3,0,1] row_mask:0xf bank_mask:0xf bound_ctrl:1
	v_add_f32_dpp v83, v83, v83 quad_perm:[2,3,0,1] row_mask:0xf bank_mask:0xf bound_ctrl:1
	v_add_f32_dpp v84, v84, v84 quad_perm:[2,3,0,1] row_mask:0xf bank_mask:0xf bound_ctrl:1
	v_add_f32_dpp v85, v85, v85 quad_perm:[2,3,0,1] row_mask:0xf bank_mask:0xf bound_ctrl:1
	v_add_f32_dpp v86, v86, v86 quad_perm:[2,3,0,1] row_mask:0xf bank_mask:0xf bound_ctrl:1
	v_add_f32_dpp v87, v87, v87 quad_perm:[2,3,0,1] row_mask:0xf bank_mask:0xf bound_ctrl:1
	s_nop 1
	v_add_f32_dpp v80, v80, v80 row_half_mirror row_mask:0xf bank_mask:0xf bound_ctrl:1
	v_add_f32_dpp v81, v81, v81 row_half_mirror row_mask:0xf bank_mask:0xf bound_ctrl:1
	v_add_f32_dpp v82, v82, v82 row_half_mirror row_mask:0xf bank_mask:0xf bound_ctrl:1
	v_add_f32_dpp v83, v83, v83 row_half_mirror row_mask:0xf bank_mask:0xf bound_ctrl:1
	v_add_f32_dpp v84, v84, v84 row_half_mirror row_mask:0xf bank_mask:0xf bound_ctrl:1
	v_add_f32_dpp v85, v85, v85 row_half_mirror row_mask:0xf bank_mask:0xf bound_ctrl:1
	v_add_f32_dpp v86, v86, v86 row_half_mirror row_mask:0xf bank_mask:0xf bound_ctrl:1
	v_add_f32_dpp v87, v87, v87 row_half_mirror row_mask:0xf bank_mask:0xf bound_ctrl:1
	s_nop 1
	v_add_f32_dpp v80, v80, v80 row_mirror row_mask:0xf bank_mask:0xf bound_ctrl:1
	v_add_f32_dpp v81, v81, v81 row_mirror row_mask:0xf bank_mask:0xf bound_ctrl:1
	v_add_f32_dpp v82, v82, v82 row_mirror row_mask:0xf bank_mask:0xf bound_ctrl:1
	v_add_f32_dpp v83, v83, v83 row_mirror row_mask:0xf bank_mask:0xf bound_ctrl:1
	v_add_f32_dpp v84, v84, v84 row_mirror row_mask:0xf bank_mask:0xf bound_ctrl:1
	v_add_f32_dpp v85, v85, v85 row_mirror row_mask:0xf bank_mask:0xf bound_ctrl:1
	v_add_f32_dpp v86, v86, v86 row_mirror row_mask:0xf bank_mask:0xf bound_ctrl:1
	v_add_f32_dpp v87, v87, v87 row_mirror row_mask:0xf bank_mask:0xf bound_ctrl:1
	v_lshrrev_b32_e32 v12, 6, v1
	v_and_b32_e32 v12, 12, v12
	s_lshl_b32 s52, s9, 4
	s_add_i32 s52, s52, 0
	v_add_u32_e32 v12, s52, v12
	s_mov_b32 exec_lo, 0x10001
	s_mov_b32 exec_hi, 0x10001
	ds_write_b32 v12, v80
	ds_write_b32 v12, v81 offset:128
	ds_write_b32 v12, v82 offset:256
	ds_write_b32 v12, v83 offset:384
	ds_write_b32 v12, v84 offset:512
	ds_write_b32 v12, v85 offset:640
	ds_write_b32 v12, v86 offset:768
	ds_write_b32 v12, v87 offset:896
	s_mov_b64 exec, -1
	s_waitcnt lgkmcnt(0)
	s_barrier
	v_lshrrev_b32_e32 v13, 4, v1
	v_and_b32_e32 v13, 7, v13
	v_lshlrev_b32_e32 v12, 7, v13
	ds_read_b128 v[88:91], v12
	ds_read_b128 v[92:95], v12 offset:16
	ds_read_b128 v[96:99], v12 offset:32
	ds_read_b128 v[100:103], v12 offset:48
	ds_read_b128 v[104:107], v12 offset:64
	ds_read_b128 v[108:111], v12 offset:80
	ds_read_b128 v[112:115], v12 offset:96
	ds_read_b128 v[116:119], v12 offset:112
	s_waitcnt lgkmcnt(0)
	v_add_f32_e32 v14, v88, v89
	v_add_f32_e32 v14, v14, v90
	v_add_f32_e32 v14, v14, v91
	v_add_f32_e32 v14, v14, v92
	v_add_f32_e32 v14, v14, v93
	v_add_f32_e32 v14, v14, v94
	v_add_f32_e32 v14, v14, v95
	v_add_f32_e32 v14, v14, v96
	v_add_f32_e32 v14, v14, v97
	v_add_f32_e32 v14, v14, v98
	v_add_f32_e32 v14, v14, v99
	v_add_f32_e32 v14, v14, v100
	v_add_f32_e32 v14, v14, v101
	v_add_f32_e32 v14, v14, v102
	v_add_f32_e32 v14, v14, v103
	v_add_f32_e32 v14, v14, v104
	v_add_f32_e32 v14, v14, v105
	v_add_f32_e32 v14, v14, v106
	v_add_f32_e32 v14, v14, v107
	v_add_f32_e32 v14, v14, v108
	v_add_f32_e32 v14, v14, v109
	v_add_f32_e32 v14, v14, v110
	v_add_f32_e32 v14, v14, v111
	v_add_f32_e32 v14, v14, v112
	v_add_f32_e32 v14, v14, v113
	v_add_f32_e32 v14, v14, v114
	v_add_f32_e32 v14, v14, v115
	v_add_f32_e32 v14, v14, v116
	v_add_f32_e32 v14, v14, v117
	v_add_f32_e32 v14, v14, v118
	v_add_f32_e32 v14, v14, v119
	v_mov_b32_e32 v221, 0x358637bd
	v_mov_b32_e32 v222, 0x260
	s_mov_b32 s54, 0xf800000
	v_fmamk_f32 v14, v14, 0x39800000, v221
	v_mul_f32_e32 v15, 0x4f800000, v14
	v_cmp_gt_f32_e32 vcc, s54, v14
	s_nop 1
	v_cndmask_b32_e32 v14, v14, v15, vcc
	v_sqrt_f32_e32 v15, v14
	s_nop 0
	v_add_u32_e32 v216, -1, v15
	v_add_u32_e32 v217, 1, v15
	v_fma_f32 v218, -v216, v15, v14
	v_fma_f32 v220, -v217, v15, v14
	v_cmp_ge_f32_e64 s[30:31], 0, v218
	s_nop 1
	v_cndmask_b32_e64 v15, v15, v216, s[30:31]
	v_cmp_lt_f32_e64 s[30:31], 0, v220
	s_nop 1
	v_cndmask_b32_e64 v15, v15, v217, s[30:31]
	v_mul_f32_e32 v216, 0x37800000, v15
	v_cndmask_b32_e32 v15, v15, v216, vcc
	v_cmp_class_f32_e32 vcc, v14, v222
	s_nop 1
	v_cndmask_b32_e32 v14, v15, v14, vcc
	v_div_scale_f32 v15, s[30:31], v14, v14, 1.0
	v_rcp_f32_e32 v216, v15
	v_div_scale_f32 v217, vcc, 1.0, v14, 1.0
	v_fma_f32 v218, -v15, v216, 1.0
	v_fmac_f32_e32 v216, v218, v216
	v_mul_f32_e32 v218, v217, v216
	v_fma_f32 v220, -v15, v218, v217
	v_fmac_f32_e32 v218, v220, v216
	v_fma_f32 v15, -v15, v218, v217
	v_div_fmas_f32 v15, v15, v216, v218
	v_div_fixup_f32 v14, v15, v14, 1.0
	s_mul_i32 s52, s9, 320
	s_lshl_b32 s53, s13, 5
	s_add_i32 s52, s52, s53
	s_add_i32 s52, s52, 0x800
	v_lshl_add_u32 v12, v13, 2, s52
	ds_write_b32 v12, v14
	s_nop 1
	v_readlane_b32 s20, v14, 0
	v_readlane_b32 s21, v14, 1
	v_readlane_b32 s22, v14, 2
	v_readlane_b32 s23, v14, 3
	v_readlane_b32 s24, v14, 4
	v_readlane_b32 s25, v14, 5
	v_readlane_b32 s26, v14, 6
	v_readlane_b32 s27, v14, 7
	s_lshl_b32 s53, s12, 2
	v_subrev_u32_e32 v216, s53, v12
	ds_read_b32 v217, v216
	v_add_u32_e32 v218, s15, v13
	v_cmp_le_u32_e32 vcc, s12, v218
	v_add_u32_e32 v218, 1, v218
	v_min_u32_e32 v218, s12, v218
	v_cvt_f32_u32_e32 v220, v218
	s_waitcnt lgkmcnt(0)
	v_cndmask_b32_e32 v217, 0, v217, vcc
	s_nop 1
	v_readlane_b32 s36, v217, 0
	v_readlane_b32 s37, v217, 1
	v_readlane_b32 s38, v217, 2
	v_readlane_b32 s39, v217, 3
	v_readlane_b32 s40, v217, 4
	v_readlane_b32 s41, v217, 5
	v_readlane_b32 s42, v217, 6
	v_readlane_b32 s43, v217, 7
	v_div_scale_f32 v15, s[30:31], v220, v220, 1.0
	v_rcp_f32_e32 v216, v15
	v_div_scale_f32 v217, vcc, 1.0, v220, 1.0
	v_fma_f32 v218, -v15, v216, 1.0
	v_fmac_f32_e32 v216, v218, v216
	v_mul_f32_e32 v218, v217, v216
	v_fma_f32 v221, -v15, v218, v217
	v_fmac_f32_e32 v218, v221, v216
	v_fma_f32 v15, -v15, v218, v217
	v_div_fmas_f32 v15, v15, v216, v218
	v_div_fixup_f32 v14, v15, v220, 1.0
	s_nop 1
	v_readlane_b32 s44, v14, 0
	v_readlane_b32 s45, v14, 1
	v_readlane_b32 s46, v14, 2
	v_readlane_b32 s47, v14, 3
	v_readlane_b32 s48, v14, 4
	v_readlane_b32 s49, v14, 5
	v_readlane_b32 s50, v14, 6
	v_readlane_b32 s51, v14, 7
	s_nop 1
	s_add_i32 s52, s14, 0
	s_sub_i32 s52, s52, s12
	s_max_i32 s52, s52, 0
	s_mov_b32 s53, 0
	s_lshl_b64 s[52:53], s[52:53], 14
	s_add_u32 s52, s52, s2
	s_addc_u32 s53, s53, s3
	global_load_dwordx4 v[144:147], v1, s[52:53]
	global_load_dwordx4 v[148:151], v1, s[52:53] offset:1024
	s_add_i32 s52, s14, 1
	s_sub_i32 s52, s52, s12
	s_max_i32 s52, s52, 0
	s_mov_b32 s53, 0
	s_lshl_b64 s[52:53], s[52:53], 14
	s_add_u32 s52, s52, s2
	s_addc_u32 s53, s53, s3
	global_load_dwordx4 v[152:155], v1, s[52:53]
	global_load_dwordx4 v[156:159], v1, s[52:53] offset:1024
	s_add_i32 s52, s14, 2
	s_sub_i32 s52, s52, s12
	s_max_i32 s52, s52, 0
	s_mov_b32 s53, 0
	s_lshl_b64 s[52:53], s[52:53], 14
	s_add_u32 s52, s52, s2
	s_addc_u32 s53, s53, s3
	global_load_dwordx4 v[160:163], v1, s[52:53]
	global_load_dwordx4 v[164:167], v1, s[52:53] offset:1024
	s_add_i32 s52, s14, 3
	s_sub_i32 s52, s52, s12
	s_max_i32 s52, s52, 0
	s_mov_b32 s53, 0
	s_lshl_b64 s[52:53], s[52:53], 14
	s_add_u32 s52, s52, s2
	s_addc_u32 s53, s53, s3
	global_load_dwordx4 v[168:171], v1, s[52:53]
	global_load_dwordx4 v[172:175], v1, s[52:53] offset:1024
	s_add_i32 s52, s14, 4
	s_sub_i32 s52, s52, s12
	s_max_i32 s52, s52, 0
	s_mov_b32 s53, 0
	s_lshl_b64 s[52:53], s[52:53], 14
	s_add_u32 s52, s52, s2
	s_addc_u32 s53, s53, s3
	global_load_dwordx4 v[176:179], v1, s[52:53]
	global_load_dwordx4 v[180:183], v1, s[52:53] offset:1024
	s_add_i32 s52, s14, 5
	s_sub_i32 s52, s52, s12
	s_max_i32 s52, s52, 0
	s_mov_b32 s53, 0
	s_lshl_b64 s[52:53], s[52:53], 14
	s_add_u32 s52, s52, s2
	s_addc_u32 s53, s53, s3
	global_load_dwordx4 v[184:187], v1, s[52:53]
	global_load_dwordx4 v[188:191], v1, s[52:53] offset:1024
	s_add_i32 s52, s14, 6
	s_sub_i32 s52, s52, s12
	s_max_i32 s52, s52, 0
	s_mov_b32 s53, 0
	s_lshl_b64 s[52:53], s[52:53], 14
	s_add_u32 s52, s52, s2
	s_addc_u32 s53, s53, s3
	global_load_dwordx4 v[192:195], v1, s[52:53]
	global_load_dwordx4 v[196:199], v1, s[52:53] offset:1024
	s_add_i32 s52, s14, 7
	s_sub_i32 s52, s52, s12
	s_max_i32 s52, s52, 0
	s_mov_b32 s53, 0
	s_lshl_b64 s[52:53], s[52:53], 14
	s_add_u32 s52, s52, s2
	s_addc_u32 s53, s53, s3
	global_load_dwordx4 v[200:203], v1, s[52:53]
	global_load_dwordx4 v[204:207], v1, s[52:53] offset:1024
	s_cmp_ge_u32 s13, 9
	s_cbranch_scc1 .Lp1f_nonext_m0
	s_add_i32 s55, s14, 8
	s_add_i32 s52, s55, 0
	s_mov_b32 s53, 0
	s_lshl_b64 s[52:53], s[52:53], 14
	s_add_u32 s52, s52, s2
	s_addc_u32 s53, s53, s3
	global_load_dwordx4 v[80:83], v1, s[52:53]
	global_load_dwordx4 v[84:87], v1, s[52:53] offset:1024
	s_add_i32 s52, s55, 1
	s_mov_b32 s53, 0
	s_lshl_b64 s[52:53], s[52:53], 14
	s_add_u32 s52, s52, s2
	s_addc_u32 s53, s53, s3
	global_load_dwordx4 v[88:91], v1, s[52:53]
	global_load_dwordx4 v[92:95], v1, s[52:53] offset:1024
	s_add_i32 s52, s55, 2
	s_mov_b32 s53, 0
	s_lshl_b64 s[52:53], s[52:53], 14
	s_add_u32 s52, s52, s2
	s_addc_u32 s53, s53, s3
	global_load_dwordx4 v[96:99], v1, s[52:53]
	global_load_dwordx4 v[100:103], v1, s[52:53] offset:1024
	s_add_i32 s52, s55, 3
	s_mov_b32 s53, 0
	s_lshl_b64 s[52:53], s[52:53], 14
	s_add_u32 s52, s52, s2
	s_addc_u32 s53, s53, s3
	global_load_dwordx4 v[104:107], v1, s[52:53]
	global_load_dwordx4 v[108:111], v1, s[52:53] offset:1024
	s_add_i32 s52, s55, 4
	s_mov_b32 s53, 0
	s_lshl_b64 s[52:53], s[52:53], 14
	s_add_u32 s52, s52, s2
	s_addc_u32 s53, s53, s3
	global_load_dwordx4 v[112:115], v1, s[52:53]
	global_load_dwordx4 v[116:119], v1, s[52:53] offset:1024
	s_add_i32 s52, s55, 5
	s_mov_b32 s53, 0
	s_lshl_b64 s[52:53], s[52:53], 14
	s_add_u32 s52, s52, s2
	s_addc_u32 s53, s53, s3
	global_load_dwordx4 v[120:123], v1, s[52:53]
	global_load_dwordx4 v[124:127], v1, s[52:53] offset:1024
	s_add_i32 s52, s55, 6
	s_mov_b32 s53, 0
	s_lshl_b64 s[52:53], s[52:53], 14
	s_add_u32 s52, s52, s2
	s_addc_u32 s53, s53, s3
	global_load_dwordx4 v[128:131], v1, s[52:53]
	global_load_dwordx4 v[132:135], v1, s[52:53] offset:1024
	s_add_i32 s52, s55, 7
	s_mov_b32 s53, 0
	s_lshl_b64 s[52:53], s[52:53], 14
	s_add_u32 s52, s52, s2
	s_addc_u32 s53, s53, s3
	global_load_dwordx4 v[136:139], v1, s[52:53]
	global_load_dwordx4 v[140:143], v1, s[52:53] offset:1024
.Lp1f_nonext_m0:
	v_mul_f32_e32 v16, s20, v16
	v_mul_f32_e32 v17, s20, v17
	v_mul_f32_e32 v18, s20, v18
	v_mul_f32_e32 v19, s20, v19
	v_mul_f32_e32 v20, s20, v20
	v_mul_f32_e32 v21, s20, v21
	v_mul_f32_e32 v22, s20, v22
	v_mul_f32_e32 v23, s20, v23
	v_pk_mul_f32 v[16:17], v[16:17], v[4:5]
	v_pk_mul_f32 v[18:19], v[18:19], v[6:7]
	v_pk_mul_f32 v[20:21], v[20:21], v[8:9]
	v_pk_mul_f32 v[22:23], v[22:23], v[10:11]
	v_mul_f32_e32 v24, s21, v24
	v_mul_f32_e32 v25, s21, v25
	v_mul_f32_e32 v26, s21, v26
	v_mul_f32_e32 v27, s21, v27
	v_mul_f32_e32 v28, s21, v28
	v_mul_f32_e32 v29, s21, v29
	v_mul_f32_e32 v30, s21, v30
	v_mul_f32_e32 v31, s21, v31
	v_pk_mul_f32 v[24:25], v[24:25], v[4:5]
	v_pk_mul_f32 v[26:27], v[26:27], v[6:7]
	v_pk_mul_f32 v[28:29], v[28:29], v[8:9]
	v_pk_mul_f32 v[30:31], v[30:31], v[10:11]
	v_mul_f32_e32 v32, s22, v32
	v_mul_f32_e32 v33, s22, v33
	v_mul_f32_e32 v34, s22, v34
	v_mul_f32_e32 v35, s22, v35
	v_mul_f32_e32 v36, s22, v36
	v_mul_f32_e32 v37, s22, v37
	v_mul_f32_e32 v38, s22, v38
	v_mul_f32_e32 v39, s22, v39
	v_pk_mul_f32 v[32:33], v[32:33], v[4:5]
	v_pk_mul_f32 v[34:35], v[34:35], v[6:7]
	v_pk_mul_f32 v[36:37], v[36:37], v[8:9]
	v_pk_mul_f32 v[38:39], v[38:39], v[10:11]
	v_mul_f32_e32 v40, s23, v40
	v_mul_f32_e32 v41, s23, v41
	v_mul_f32_e32 v42, s23, v42
	v_mul_f32_e32 v43, s23, v43
	v_mul_f32_e32 v44, s23, v44
	v_mul_f32_e32 v45, s23, v45
	v_mul_f32_e32 v46, s23, v46
	v_mul_f32_e32 v47, s23, v47
	v_pk_mul_f32 v[40:41], v[40:41], v[4:5]
	v_pk_mul_f32 v[42:43], v[42:43], v[6:7]
	v_pk_mul_f32 v[44:45], v[44:45], v[8:9]
	v_pk_mul_f32 v[46:47], v[46:47], v[10:11]
	v_mul_f32_e32 v48, s24, v48
	v_mul_f32_e32 v49, s24, v49
	v_mul_f32_e32 v50, s24, v50
	v_mul_f32_e32 v51, s24, v51
	v_mul_f32_e32 v52, s24, v52
	v_mul_f32_e32 v53, s24, v53
	v_mul_f32_e32 v54, s24, v54
	v_mul_f32_e32 v55, s24, v55
	v_pk_mul_f32 v[48:49], v[48:49], v[4:5]
	v_pk_mul_f32 v[50:51], v[50:51], v[6:7]
	v_pk_mul_f32 v[52:53], v[52:53], v[8:9]
	v_pk_mul_f32 v[54:55], v[54:55], v[10:11]
	v_mul_f32_e32 v56, s25, v56
	v_mul_f32_e32 v57, s25, v57
	v_mul_f32_e32 v58, s25, v58
	v_mul_f32_e32 v59, s25, v59
	v_mul_f32_e32 v60, s25, v60
	v_mul_f32_e32 v61, s25, v61
	v_mul_f32_e32 v62, s25, v62
	v_mul_f32_e32 v63, s25, v63
	v_pk_mul_f32 v[56:57], v[56:57], v[4:5]
	v_pk_mul_f32 v[58:59], v[58:59], v[6:7]
	v_pk_mul_f32 v[60:61], v[60:61], v[8:9]
	v_pk_mul_f32 v[62:63], v[62:63], v[10:11]
	v_mul_f32_e32 v64, s26, v64
	v_mul_f32_e32 v65, s26, v65
	v_mul_f32_e32 v66, s26, v66
	v_mul_f32_e32 v67, s26, v67
	v_mul_f32_e32 v68, s26, v68
	v_mul_f32_e32 v69, s26, v69
	v_mul_f32_e32 v70, s26, v70
	v_mul_f32_e32 v71, s26, v71
	v_pk_mul_f32 v[64:65], v[64:65], v[4:5]
	v_pk_mul_f32 v[66:67], v[66:67], v[6:7]
	v_pk_mul_f32 v[68:69], v[68:69], v[8:9]
	v_pk_mul_f32 v[70:71], v[70:71], v[10:11]
	v_mul_f32_e32 v72, s27, v72
	v_mul_f32_e32 v73, s27, v73
	v_mul_f32_e32 v74, s27, v74
	v_mul_f32_e32 v75, s27, v75
	v_mul_f32_e32 v76, s27, v76
	v_mul_f32_e32 v77, s27, v77
	v_mul_f32_e32 v78, s27, v78
	v_mul_f32_e32 v79, s27, v79
	v_pk_mul_f32 v[72:73], v[72:73], v[4:5]
	v_pk_mul_f32 v[74:75], v[74:75], v[6:7]
	v_pk_mul_f32 v[76:77], v[76:77], v[8:9]
	v_pk_mul_f32 v[78:79], v[78:79], v[10:11]
	s_cmp_ge_u32 s13, 9
	s_cbranch_scc1 .Lp1f_w0_m0
	s_waitcnt vmcnt(16)
	s_branch .Lp1f_w1_m0

.Lp1f_w1_m0:
	v_mul_f32_e32 v144, s36, v144
	v_mul_f32_e32 v145, s36, v145
	v_mul_f32_e32 v146, s36, v146
	v_mul_f32_e32 v147, s36, v147
	v_mul_f32_e32 v148, s36, v148
	v_mul_f32_e32 v149, s36, v149
	v_mul_f32_e32 v150, s36, v150
	v_mul_f32_e32 v151, s36, v151
	v_pk_mul_f32 v[144:145], v[144:145], v[4:5]
	v_pk_mul_f32 v[146:147], v[146:147], v[6:7]
	v_pk_mul_f32 v[148:149], v[148:149], v[8:9]
	v_pk_mul_f32 v[150:151], v[150:151], v[10:11]
	v_mul_f32_e32 v152, s37, v152
	v_mul_f32_e32 v153, s37, v153
	v_mul_f32_e32 v154, s37, v154
	v_mul_f32_e32 v155, s37, v155
	v_mul_f32_e32 v156, s37, v156
	v_mul_f32_e32 v157, s37, v157
	v_mul_f32_e32 v158, s37, v158
	v_mul_f32_e32 v159, s37, v159
	v_pk_mul_f32 v[152:153], v[152:153], v[4:5]
	v_pk_mul_f32 v[154:155], v[154:155], v[6:7]
	v_pk_mul_f32 v[156:157], v[156:157], v[8:9]
	v_pk_mul_f32 v[158:159], v[158:159], v[10:11]
	v_mul_f32_e32 v160, s38, v160
	v_mul_f32_e32 v161, s38, v161
	v_mul_f32_e32 v162, s38, v162
	v_mul_f32_e32 v163, s38, v163
	v_mul_f32_e32 v164, s38, v164
	v_mul_f32_e32 v165, s38, v165
	v_mul_f32_e32 v166, s38, v166
	v_mul_f32_e32 v167, s38, v167
	v_pk_mul_f32 v[160:161], v[160:161], v[4:5]
	v_pk_mul_f32 v[162:163], v[162:163], v[6:7]
	v_pk_mul_f32 v[164:165], v[164:165], v[8:9]
	v_pk_mul_f32 v[166:167], v[166:167], v[10:11]
	v_mul_f32_e32 v168, s39, v168
	v_mul_f32_e32 v169, s39, v169
	v_mul_f32_e32 v170, s39, v170
	v_mul_f32_e32 v171, s39, v171
	v_mul_f32_e32 v172, s39, v172
	v_mul_f32_e32 v173, s39, v173
	v_mul_f32_e32 v174, s39, v174
	v_mul_f32_e32 v175, s39, v175
	v_pk_mul_f32 v[168:169], v[168:169], v[4:5]
	v_pk_mul_f32 v[170:171], v[170:171], v[6:7]
	v_pk_mul_f32 v[172:173], v[172:173], v[8:9]
	v_pk_mul_f32 v[174:175], v[174:175], v[10:11]
	v_mul_f32_e32 v176, s40, v176
	v_mul_f32_e32 v177, s40, v177
	v_mul_f32_e32 v178, s40, v178
	v_mul_f32_e32 v179, s40, v179
	v_mul_f32_e32 v180, s40, v180
	v_mul_f32_e32 v181, s40, v181
	v_mul_f32_e32 v182, s40, v182
	v_mul_f32_e32 v183, s40, v183
	v_pk_mul_f32 v[176:177], v[176:177], v[4:5]
	v_pk_mul_f32 v[178:179], v[178:179], v[6:7]
	v_pk_mul_f32 v[180:181], v[180:181], v[8:9]
	v_pk_mul_f32 v[182:183], v[182:183], v[10:11]
	v_mul_f32_e32 v184, s41, v184
	v_mul_f32_e32 v185, s41, v185
	v_mul_f32_e32 v186, s41, v186
	v_mul_f32_e32 v187, s41, v187
	v_mul_f32_e32 v188, s41, v188
	v_mul_f32_e32 v189, s41, v189
	v_mul_f32_e32 v190, s41, v190
	v_mul_f32_e32 v191, s41, v191
	v_pk_mul_f32 v[184:185], v[184:185], v[4:5]
	v_pk_mul_f32 v[186:187], v[186:187], v[6:7]
	v_pk_mul_f32 v[188:189], v[188:189], v[8:9]
	v_pk_mul_f32 v[190:191], v[190:191], v[10:11]
	v_mul_f32_e32 v192, s42, v192
	v_mul_f32_e32 v193, s42, v193
	v_mul_f32_e32 v194, s42, v194
	v_mul_f32_e32 v195, s42, v195
	v_mul_f32_e32 v196, s42, v196
	v_mul_f32_e32 v197, s42, v197
	v_mul_f32_e32 v198, s42, v198
	v_mul_f32_e32 v199, s42, v199
	v_pk_mul_f32 v[192:193], v[192:193], v[4:5]
	v_pk_mul_f32 v[194:195], v[194:195], v[6:7]
	v_pk_mul_f32 v[196:197], v[196:197], v[8:9]
	v_pk_mul_f32 v[198:199], v[198:199], v[10:11]
	v_mul_f32_e32 v200, s43, v200
	v_mul_f32_e32 v201, s43, v201
	v_mul_f32_e32 v202, s43, v202
	v_mul_f32_e32 v203, s43, v203
	v_mul_f32_e32 v204, s43, v204
	v_mul_f32_e32 v205, s43, v205
	v_mul_f32_e32 v206, s43, v206
	v_mul_f32_e32 v207, s43, v207
	v_pk_mul_f32 v[200:201], v[200:201], v[4:5]
	v_pk_mul_f32 v[202:203], v[202:203], v[6:7]
	v_pk_mul_f32 v[204:205], v[204:205], v[8:9]
	v_pk_mul_f32 v[206:207], v[206:207], v[10:11]
	v_pk_add_f32 v[208:209], v[208:209], v[16:17]
	v_pk_add_f32 v[210:211], v[210:211], v[18:19]
	v_pk_add_f32 v[212:213], v[212:213], v[20:21]
	v_pk_add_f32 v[214:215], v[214:215], v[22:23]
	v_pk_add_f32 v[208:209], v[208:209], v[144:145] neg_lo:[0,1] neg_hi:[0,1]
	v_pk_add_f32 v[210:211], v[210:211], v[146:147] neg_lo:[0,1] neg_hi:[0,1]
	v_pk_add_f32 v[212:213], v[212:213], v[148:149] neg_lo:[0,1] neg_hi:[0,1]
	v_pk_add_f32 v[214:215], v[214:215], v[150:151] neg_lo:[0,1] neg_hi:[0,1]
	v_fma_f32 v12, v208, s44, -v16
	v_fma_f32 v13, v209, s44, -v17
	v_fma_f32 v14, v210, s44, -v18
	v_fma_f32 v15, v211, s44, -v19
	v_fma_f32 v216, v212, s44, -v20
	v_fma_f32 v217, v213, s44, -v21
	v_fma_f32 v218, v214, s44, -v22
	v_fma_f32 v220, v215, s44, -v23
	v_cvt_pk_bf16_f32 v144, v12, v13
	v_cvt_pk_bf16_f32 v145, v14, v15
	v_cvt_pk_bf16_f32 v146, v216, v217
	v_cvt_pk_bf16_f32 v147, v218, v220
	s_add_i32 s52, s14, 0
	s_mov_b32 s53, 0
	s_lshl_b64 s[52:53], s[52:53], 13
	s_add_u32 s52, s52, s4
	s_addc_u32 s53, s53, s5
	global_store_dwordx2 v3, v[144:145], s[52:53]
	global_store_dwordx2 v3, v[146:147], s[52:53] offset:512
	v_pk_add_f32 v[208:209], v[208:209], v[24:25]
	v_pk_add_f32 v[210:211], v[210:211], v[26:27]
	v_pk_add_f32 v[212:213], v[212:213], v[28:29]
	v_pk_add_f32 v[214:215], v[214:215], v[30:31]
	v_pk_add_f32 v[208:209], v[208:209], v[152:153] neg_lo:[0,1] neg_hi:[0,1]
	v_pk_add_f32 v[210:211], v[210:211], v[154:155] neg_lo:[0,1] neg_hi:[0,1]
	v_pk_add_f32 v[212:213], v[212:213], v[156:157] neg_lo:[0,1] neg_hi:[0,1]
	v_pk_add_f32 v[214:215], v[214:215], v[158:159] neg_lo:[0,1] neg_hi:[0,1]
	v_fma_f32 v12, v208, s45, -v24
	v_fma_f32 v13, v209, s45, -v25
	v_fma_f32 v14, v210, s45, -v26
	v_fma_f32 v15, v211, s45, -v27
	v_fma_f32 v216, v212, s45, -v28
	v_fma_f32 v217, v213, s45, -v29
	v_fma_f32 v218, v214, s45, -v30
	v_fma_f32 v220, v215, s45, -v31
	v_cvt_pk_bf16_f32 v152, v12, v13
	v_cvt_pk_bf16_f32 v153, v14, v15
	v_cvt_pk_bf16_f32 v154, v216, v217
	v_cvt_pk_bf16_f32 v155, v218, v220
	s_add_i32 s52, s14, 1
	s_mov_b32 s53, 0
	s_lshl_b64 s[52:53], s[52:53], 13
	s_add_u32 s52, s52, s4
	s_addc_u32 s53, s53, s5
	global_store_dwordx2 v3, v[152:153], s[52:53]
	global_store_dwordx2 v3, v[154:155], s[52:53] offset:512
	v_pk_add_f32 v[208:209], v[208:209], v[32:33]
	v_pk_add_f32 v[210:211], v[210:211], v[34:35]
	v_pk_add_f32 v[212:213], v[212:213], v[36:37]
	v_pk_add_f32 v[214:215], v[214:215], v[38:39]
	v_pk_add_f32 v[208:209], v[208:209], v[160:161] neg_lo:[0,1] neg_hi:[0,1]
	v_pk_add_f32 v[210:211], v[210:211], v[162:163] neg_lo:[0,1] neg_hi:[0,1]
	v_pk_add_f32 v[212:213], v[212:213], v[164:165] neg_lo:[0,1] neg_hi:[0,1]
	v_pk_add_f32 v[214:215], v[214:215], v[166:167] neg_lo:[0,1] neg_hi:[0,1]
	v_fma_f32 v12, v208, s46, -v32
	v_fma_f32 v13, v209, s46, -v33
	v_fma_f32 v14, v210, s46, -v34
	v_fma_f32 v15, v211, s46, -v35
	v_fma_f32 v216, v212, s46, -v36
	v_fma_f32 v217, v213, s46, -v37
	v_fma_f32 v218, v214, s46, -v38
	v_fma_f32 v220, v215, s46, -v39
	v_cvt_pk_bf16_f32 v160, v12, v13
	v_cvt_pk_bf16_f32 v161, v14, v15
	v_cvt_pk_bf16_f32 v162, v216, v217
	v_cvt_pk_bf16_f32 v163, v218, v220
	s_add_i32 s52, s14, 2
	s_mov_b32 s53, 0
	s_lshl_b64 s[52:53], s[52:53], 13
	s_add_u32 s52, s52, s4
	s_addc_u32 s53, s53, s5
	global_store_dwordx2 v3, v[160:161], s[52:53]
	global_store_dwordx2 v3, v[162:163], s[52:53] offset:512
	v_pk_add_f32 v[208:209], v[208:209], v[40:41]
	v_pk_add_f32 v[210:211], v[210:211], v[42:43]
	v_pk_add_f32 v[212:213], v[212:213], v[44:45]
	v_pk_add_f32 v[214:215], v[214:215], v[46:47]
	v_pk_add_f32 v[208:209], v[208:209], v[168:169] neg_lo:[0,1] neg_hi:[0,1]
	v_pk_add_f32 v[210:211], v[210:211], v[170:171] neg_lo:[0,1] neg_hi:[0,1]
	v_pk_add_f32 v[212:213], v[212:213], v[172:173] neg_lo:[0,1] neg_hi:[0,1]
	v_pk_add_f32 v[214:215], v[214:215], v[174:175] neg_lo:[0,1] neg_hi:[0,1]
	v_fma_f32 v12, v208, s47, -v40
	v_fma_f32 v13, v209, s47, -v41
	v_fma_f32 v14, v210, s47, -v42
	v_fma_f32 v15, v211, s47, -v43
	v_fma_f32 v216, v212, s47, -v44
	v_fma_f32 v217, v213, s47, -v45
	v_fma_f32 v218, v214, s47, -v46
	v_fma_f32 v220, v215, s47, -v47
	v_cvt_pk_bf16_f32 v168, v12, v13
	v_cvt_pk_bf16_f32 v169, v14, v15
	v_cvt_pk_bf16_f32 v170, v216, v217
	v_cvt_pk_bf16_f32 v171, v218, v220
	s_add_i32 s52, s14, 3
	s_mov_b32 s53, 0
	s_lshl_b64 s[52:53], s[52:53], 13
	s_add_u32 s52, s52, s4
	s_addc_u32 s53, s53, s5
	global_store_dwordx2 v3, v[168:169], s[52:53]
	global_store_dwordx2 v3, v[170:171], s[52:53] offset:512
	v_pk_add_f32 v[208:209], v[208:209], v[48:49]
	v_pk_add_f32 v[210:211], v[210:211], v[50:51]
	v_pk_add_f32 v[212:213], v[212:213], v[52:53]
	v_pk_add_f32 v[214:215], v[214:215], v[54:55]
	v_pk_add_f32 v[208:209], v[208:209], v[176:177] neg_lo:[0,1] neg_hi:[0,1]
	v_pk_add_f32 v[210:211], v[210:211], v[178:179] neg_lo:[0,1] neg_hi:[0,1]
	v_pk_add_f32 v[212:213], v[212:213], v[180:181] neg_lo:[0,1] neg_hi:[0,1]
	v_pk_add_f32 v[214:215], v[214:215], v[182:183] neg_lo:[0,1] neg_hi:[0,1]
	v_fma_f32 v12, v208, s48, -v48
	v_fma_f32 v13, v209, s48, -v49
	v_fma_f32 v14, v210, s48, -v50
	v_fma_f32 v15, v211, s48, -v51
	v_fma_f32 v216, v212, s48, -v52
	v_fma_f32 v217, v213, s48, -v53
	v_fma_f32 v218, v214, s48, -v54
	v_fma_f32 v220, v215, s48, -v55
	v_cvt_pk_bf16_f32 v176, v12, v13
	v_cvt_pk_bf16_f32 v177, v14, v15
	v_cvt_pk_bf16_f32 v178, v216, v217
	v_cvt_pk_bf16_f32 v179, v218, v220
	s_add_i32 s52, s14, 4
	s_mov_b32 s53, 0
	s_lshl_b64 s[52:53], s[52:53], 13
	s_add_u32 s52, s52, s4
	s_addc_u32 s53, s53, s5
	global_store_dwordx2 v3, v[176:177], s[52:53]
	global_store_dwordx2 v3, v[178:179], s[52:53] offset:512
	v_pk_add_f32 v[208:209], v[208:209], v[56:57]
	v_pk_add_f32 v[210:211], v[210:211], v[58:59]
	v_pk_add_f32 v[212:213], v[212:213], v[60:61]
	v_pk_add_f32 v[214:215], v[214:215], v[62:63]
	v_pk_add_f32 v[208:209], v[208:209], v[184:185] neg_lo:[0,1] neg_hi:[0,1]
	v_pk_add_f32 v[210:211], v[210:211], v[186:187] neg_lo:[0,1] neg_hi:[0,1]
	v_pk_add_f32 v[212:213], v[212:213], v[188:189] neg_lo:[0,1] neg_hi:[0,1]
	v_pk_add_f32 v[214:215], v[214:215], v[190:191] neg_lo:[0,1] neg_hi:[0,1]
	v_fma_f32 v12, v208, s49, -v56
	v_fma_f32 v13, v209, s49, -v57
	v_fma_f32 v14, v210, s49, -v58
	v_fma_f32 v15, v211, s49, -v59
	v_fma_f32 v216, v212, s49, -v60
	v_fma_f32 v217, v213, s49, -v61
	v_fma_f32 v218, v214, s49, -v62
	v_fma_f32 v220, v215, s49, -v63
	v_cvt_pk_bf16_f32 v184, v12, v13
	v_cvt_pk_bf16_f32 v185, v14, v15
	v_cvt_pk_bf16_f32 v186, v216, v217
	v_cvt_pk_bf16_f32 v187, v218, v220
	s_add_i32 s52, s14, 5
	s_mov_b32 s53, 0
	s_lshl_b64 s[52:53], s[52:53], 13
	s_add_u32 s52, s52, s4
	s_addc_u32 s53, s53, s5
	global_store_dwordx2 v3, v[184:185], s[52:53]
	global_store_dwordx2 v3, v[186:187], s[52:53] offset:512
	v_pk_add_f32 v[208:209], v[208:209], v[64:65]
	v_pk_add_f32 v[210:211], v[210:211], v[66:67]
	v_pk_add_f32 v[212:213], v[212:213], v[68:69]
	v_pk_add_f32 v[214:215], v[214:215], v[70:71]
	v_pk_add_f32 v[208:209], v[208:209], v[192:193] neg_lo:[0,1] neg_hi:[0,1]
	v_pk_add_f32 v[210:211], v[210:211], v[194:195] neg_lo:[0,1] neg_hi:[0,1]
	v_pk_add_f32 v[212:213], v[212:213], v[196:197] neg_lo:[0,1] neg_hi:[0,1]
	v_pk_add_f32 v[214:215], v[214:215], v[198:199] neg_lo:[0,1] neg_hi:[0,1]
	v_fma_f32 v12, v208, s50, -v64
	v_fma_f32 v13, v209, s50, -v65
	v_fma_f32 v14, v210, s50, -v66
	v_fma_f32 v15, v211, s50, -v67
	v_fma_f32 v216, v212, s50, -v68
	v_fma_f32 v217, v213, s50, -v69
	v_fma_f32 v218, v214, s50, -v70
	v_fma_f32 v220, v215, s50, -v71
	v_cvt_pk_bf16_f32 v192, v12, v13
	v_cvt_pk_bf16_f32 v193, v14, v15
	v_cvt_pk_bf16_f32 v194, v216, v217
	v_cvt_pk_bf16_f32 v195, v218, v220
	s_add_i32 s52, s14, 6
	s_mov_b32 s53, 0
	s_lshl_b64 s[52:53], s[52:53], 13
	s_add_u32 s52, s52, s4
	s_addc_u32 s53, s53, s5
	global_store_dwordx2 v3, v[192:193], s[52:53]
	global_store_dwordx2 v3, v[194:195], s[52:53] offset:512
	v_pk_add_f32 v[208:209], v[208:209], v[72:73]
	v_pk_add_f32 v[210:211], v[210:211], v[74:75]
	v_pk_add_f32 v[212:213], v[212:213], v[76:77]
	v_pk_add_f32 v[214:215], v[214:215], v[78:79]
	v_pk_add_f32 v[208:209], v[208:209], v[200:201] neg_lo:[0,1] neg_hi:[0,1]
	v_pk_add_f32 v[210:211], v[210:211], v[202:203] neg_lo:[0,1] neg_hi:[0,1]
	v_pk_add_f32 v[212:213], v[212:213], v[204:205] neg_lo:[0,1] neg_hi:[0,1]
	v_pk_add_f32 v[214:215], v[214:215], v[206:207] neg_lo:[0,1] neg_hi:[0,1]
	v_fma_f32 v12, v208, s51, -v72
	v_fma_f32 v13, v209, s51, -v73
	v_fma_f32 v14, v210, s51, -v74
	v_fma_f32 v15, v211, s51, -v75
	v_fma_f32 v216, v212, s51, -v76
	v_fma_f32 v217, v213, s51, -v77
	v_fma_f32 v218, v214, s51, -v78
	v_fma_f32 v220, v215, s51, -v79
	v_cvt_pk_bf16_f32 v200, v12, v13
	v_cvt_pk_bf16_f32 v201, v14, v15
	v_cvt_pk_bf16_f32 v202, v216, v217
	v_cvt_pk_bf16_f32 v203, v218, v220
	s_add_i32 s52, s14, 7
	s_mov_b32 s53, 0
	s_lshl_b64 s[52:53], s[52:53], 13
	s_add_u32 s52, s52, s4
	s_addc_u32 s53, s53, s5
	global_store_dwordx2 v3, v[200:201], s[52:53]
	global_store_dwordx2 v3, v[202:203], s[52:53] offset:512
	s_add_i32 s13, s13, 1
	s_add_i32 s14, s14, 8
	s_add_i32 s15, s15, 8
	s_waitcnt vmcnt(16)
	v_mul_f32_e32 v16, v80, v80
	v_fmac_f32_e32 v16, v81, v81
	v_fmac_f32_e32 v16, v82, v82
	v_fmac_f32_e32 v16, v83, v83
	v_fmac_f32_e32 v16, v84, v84
	v_fmac_f32_e32 v16, v85, v85
	v_fmac_f32_e32 v16, v86, v86
	v_fmac_f32_e32 v16, v87, v87
	v_mul_f32_e32 v17, v88, v88
	v_fmac_f32_e32 v17, v89, v89
	v_fmac_f32_e32 v17, v90, v90
	v_fmac_f32_e32 v17, v91, v91
	v_fmac_f32_e32 v17, v92, v92
	v_fmac_f32_e32 v17, v93, v93
	v_fmac_f32_e32 v17, v94, v94
	v_fmac_f32_e32 v17, v95, v95
	v_mul_f32_e32 v18, v96, v96
	v_fmac_f32_e32 v18, v97, v97
	v_fmac_f32_e32 v18, v98, v98
	v_fmac_f32_e32 v18, v99, v99
	v_fmac_f32_e32 v18, v100, v100
	v_fmac_f32_e32 v18, v101, v101
	v_fmac_f32_e32 v18, v102, v102
	v_fmac_f32_e32 v18, v103, v103
	v_mul_f32_e32 v19, v104, v104
	v_fmac_f32_e32 v19, v105, v105
	v_fmac_f32_e32 v19, v106, v106
	v_fmac_f32_e32 v19, v107, v107
	v_fmac_f32_e32 v19, v108, v108
	v_fmac_f32_e32 v19, v109, v109
	v_fmac_f32_e32 v19, v110, v110
	v_fmac_f32_e32 v19, v111, v111
	v_mul_f32_e32 v20, v112, v112
	v_fmac_f32_e32 v20, v113, v113
	v_fmac_f32_e32 v20, v114, v114
	v_fmac_f32_e32 v20, v115, v115
	v_fmac_f32_e32 v20, v116, v116
	v_fmac_f32_e32 v20, v117, v117
	v_fmac_f32_e32 v20, v118, v118
	v_fmac_f32_e32 v20, v119, v119
	v_mul_f32_e32 v21, v120, v120
	v_fmac_f32_e32 v21, v121, v121
	v_fmac_f32_e32 v21, v122, v122
	v_fmac_f32_e32 v21, v123, v123
	v_fmac_f32_e32 v21, v124, v124
	v_fmac_f32_e32 v21, v125, v125
	v_fmac_f32_e32 v21, v126, v126
	v_fmac_f32_e32 v21, v127, v127
	v_mul_f32_e32 v22, v128, v128
	v_fmac_f32_e32 v22, v129, v129
	v_fmac_f32_e32 v22, v130, v130
	v_fmac_f32_e32 v22, v131, v131
	v_fmac_f32_e32 v22, v132, v132
	v_fmac_f32_e32 v22, v133, v133
	v_fmac_f32_e32 v22, v134, v134
	v_fmac_f32_e32 v22, v135, v135
	v_mul_f32_e32 v23, v136, v136
	v_fmac_f32_e32 v23, v137, v137
	v_fmac_f32_e32 v23, v138, v138
	v_fmac_f32_e32 v23, v139, v139
	v_fmac_f32_e32 v23, v140, v140
	v_fmac_f32_e32 v23, v141, v141
	v_fmac_f32_e32 v23, v142, v142
	v_fmac_f32_e32 v23, v143, v143
	s_nop 1
	v_add_f32_dpp v16, v16, v16 quad_perm:[1,0,3,2] row_mask:0xf bank_mask:0xf bound_ctrl:1
	v_add_f32_dpp v17, v17, v17 quad_perm:[1,0,3,2] row_mask:0xf bank_mask:0xf bound_ctrl:1
	v_add_f32_dpp v18, v18, v18 quad_perm:[1,0,3,2] row_mask:0xf bank_mask:0xf bound_ctrl:1
	v_add_f32_dpp v19, v19, v19 quad_perm:[1,0,3,2] row_mask:0xf bank_mask:0xf bound_ctrl:1
	v_add_f32_dpp v20, v20, v20 quad_perm:[1,0,3,2] row_mask:0xf bank_mask:0xf bound_ctrl:1
	v_add_f32_dpp v21, v21, v21 quad_perm:[1,0,3,2] row_mask:0xf bank_mask:0xf bound_ctrl:1
	v_add_f32_dpp v22, v22, v22 quad_perm:[1,0,3,2] row_mask:0xf bank_mask:0xf bound_ctrl:1
	v_add_f32_dpp v23, v23, v23 quad_perm:[1,0,3,2] row_mask:0xf bank_mask:0xf bound_ctrl:1
	s_nop 1
	v_add_f32_dpp v16, v16, v16 quad_perm:[2,3,0,1] row_mask:0xf bank_mask:0xf bound_ctrl:1
	v_add_f32_dpp v17, v17, v17 quad_perm:[2,3,0,1] row_mask:0xf bank_mask:0xf bound_ctrl:1
	v_add_f32_dpp v18, v18, v18 quad_perm:[2,3,0,1] row_mask:0xf bank_mask:0xf bound_ctrl:1
	v_add_f32_dpp v19, v19, v19 quad_perm:[2,3,0,1] row_mask:0xf bank_mask:0xf bound_ctrl:1
	v_add_f32_dpp v20, v20, v20 quad_perm:[2,3,0,1] row_mask:0xf bank_mask:0xf bound_ctrl:1
	v_add_f32_dpp v21, v21, v21 quad_perm:[2,3,0,1] row_mask:0xf bank_mask:0xf bound_ctrl:1
	v_add_f32_dpp v22, v22, v22 quad_perm:[2,3,0,1] row_mask:0xf bank_mask:0xf bound_ctrl:1
	v_add_f32_dpp v23, v23, v23 quad_perm:[2,3,0,1] row_mask:0xf bank_mask:0xf bound_ctrl:1
	s_nop 1
	v_add_f32_dpp v16, v16, v16 row_half_mirror row_mask:0xf bank_mask:0xf bound_ctrl:1
	v_add_f32_dpp v17, v17, v17 row_half_mirror row_mask:0xf bank_mask:0xf bound_ctrl:1
	v_add_f32_dpp v18, v18, v18 row_half_mirror row_mask:0xf bank_mask:0xf bound_ctrl:1
	v_add_f32_dpp v19, v19, v19 row_half_mirror row_mask:0xf bank_mask:0xf bound_ctrl:1
	v_add_f32_dpp v20, v20, v20 row_half_mirror row_mask:0xf bank_mask:0xf bound_ctrl:1
	v_add_f32_dpp v21, v21, v21 row_half_mirror row_mask:0xf bank_mask:0xf bound_ctrl:1
	v_add_f32_dpp v22, v22, v22 row_half_mirror row_mask:0xf bank_mask:0xf bound_ctrl:1
	v_add_f32_dpp v23, v23, v23 row_half_mirror row_mask:0xf bank_mask:0xf bound_ctrl:1
	s_nop 1
	v_add_f32_dpp v16, v16, v16 row_mirror row_mask:0xf bank_mask:0xf bound_ctrl:1
	v_add_f32_dpp v17, v17, v17 row_mirror row_mask:0xf bank_mask:0xf bound_ctrl:1
	v_add_f32_dpp v18, v18, v18 row_mirror row_mask:0xf bank_mask:0xf bound_ctrl:1
	v_add_f32_dpp v19, v19, v19 row_mirror row_mask:0xf bank_mask:0xf bound_ctrl:1
	v_add_f32_dpp v20, v20, v20 row_mirror row_mask:0xf bank_mask:0xf bound_ctrl:1
	v_add_f32_dpp v21, v21, v21 row_mirror row_mask:0xf bank_mask:0xf bound_ctrl:1
	v_add_f32_dpp v22, v22, v22 row_mirror row_mask:0xf bank_mask:0xf bound_ctrl:1
	v_add_f32_dpp v23, v23, v23 row_mirror row_mask:0xf bank_mask:0xf bound_ctrl:1
	v_lshrrev_b32_e32 v12, 6, v1
	v_and_b32_e32 v12, 12, v12
	s_lshl_b32 s52, s9, 4
	s_add_i32 s52, s52, 1024
	v_add_u32_e32 v12, s52, v12
	s_mov_b32 exec_lo, 0x10001
	s_mov_b32 exec_hi, 0x10001
	ds_write_b32 v12, v16
	ds_write_b32 v12, v17 offset:128
	ds_write_b32 v12, v18 offset:256
	ds_write_b32 v12, v19 offset:384
	ds_write_b32 v12, v20 offset:512
	ds_write_b32 v12, v21 offset:640
	ds_write_b32 v12, v22 offset:768
	ds_write_b32 v12, v23 offset:896
	s_mov_b64 exec, -1
	s_waitcnt lgkmcnt(0)
	s_barrier
	v_lshrrev_b32_e32 v13, 4, v1
	v_and_b32_e32 v13, 7, v13
	v_lshlrev_b32_e32 v12, 7, v13
	v_add_u32_e32 v12, 0x400, v12
	ds_read_b128 v[24:27], v12
	ds_read_b128 v[28:31], v12 offset:16
	ds_read_b128 v[32:35], v12 offset:32
	ds_read_b128 v[36:39], v12 offset:48
	ds_read_b128 v[40:43], v12 offset:64
	ds_read_b128 v[44:47], v12 offset:80
	ds_read_b128 v[48:51], v12 offset:96
	ds_read_b128 v[52:55], v12 offset:112
	s_waitcnt lgkmcnt(0)
	v_add_f32_e32 v14, v24, v25
	v_add_f32_e32 v14, v14, v26
	v_add_f32_e32 v14, v14, v27
	v_add_f32_e32 v14, v14, v28
	v_add_f32_e32 v14, v14, v29
	v_add_f32_e32 v14, v14, v30
	v_add_f32_e32 v14, v14, v31
	v_add_f32_e32 v14, v14, v32
	v_add_f32_e32 v14, v14, v33
	v_add_f32_e32 v14, v14, v34
	v_add_f32_e32 v14, v14, v35
	v_add_f32_e32 v14, v14, v36
	v_add_f32_e32 v14, v14, v37
	v_add_f32_e32 v14, v14, v38
	v_add_f32_e32 v14, v14, v39
	v_add_f32_e32 v14, v14, v40
	v_add_f32_e32 v14, v14, v41
	v_add_f32_e32 v14, v14, v42
	v_add_f32_e32 v14, v14, v43
	v_add_f32_e32 v14, v14, v44
	v_add_f32_e32 v14, v14, v45
	v_add_f32_e32 v14, v14, v46
	v_add_f32_e32 v14, v14, v47
	v_add_f32_e32 v14, v14, v48
	v_add_f32_e32 v14, v14, v49
	v_add_f32_e32 v14, v14, v50
	v_add_f32_e32 v14, v14, v51
	v_add_f32_e32 v14, v14, v52
	v_add_f32_e32 v14, v14, v53
	v_add_f32_e32 v14, v14, v54
	v_add_f32_e32 v14, v14, v55
	v_mov_b32_e32 v221, 0x358637bd
	v_mov_b32_e32 v222, 0x260
	s_mov_b32 s54, 0xf800000
	v_fmamk_f32 v14, v14, 0x39800000, v221
	v_mul_f32_e32 v15, 0x4f800000, v14
	v_cmp_gt_f32_e32 vcc, s54, v14
	s_nop 1
	v_cndmask_b32_e32 v14, v14, v15, vcc
	v_sqrt_f32_e32 v15, v14
	s_nop 0
	v_add_u32_e32 v216, -1, v15
	v_add_u32_e32 v217, 1, v15
	v_fma_f32 v218, -v216, v15, v14
	v_fma_f32 v220, -v217, v15, v14
	v_cmp_ge_f32_e64 s[30:31], 0, v218
	s_nop 1
	v_cndmask_b32_e64 v15, v15, v216, s[30:31]
	v_cmp_lt_f32_e64 s[30:31], 0, v220
	s_nop 1
	v_cndmask_b32_e64 v15, v15, v217, s[30:31]
	v_mul_f32_e32 v216, 0x37800000, v15
	v_cndmask_b32_e32 v15, v15, v216, vcc
	v_cmp_class_f32_e32 vcc, v14, v222
	s_nop 1
	v_cndmask_b32_e32 v14, v15, v14, vcc
	v_div_scale_f32 v15, s[30:31], v14, v14, 1.0
	v_rcp_f32_e32 v216, v15
	v_div_scale_f32 v217, vcc, 1.0, v14, 1.0
	v_fma_f32 v218, -v15, v216, 1.0
	v_fmac_f32_e32 v216, v218, v216
	v_mul_f32_e32 v218, v217, v216
	v_fma_f32 v220, -v15, v218, v217
	v_fmac_f32_e32 v218, v220, v216
	v_fma_f32 v15, -v15, v218, v217
	v_div_fmas_f32 v15, v15, v216, v218
	v_div_fixup_f32 v14, v15, v14, 1.0
	s_mul_i32 s52, s9, 320
	s_lshl_b32 s53, s13, 5
	s_add_i32 s52, s52, s53
	s_add_i32 s52, s52, 0x800
	v_lshl_add_u32 v12, v13, 2, s52
	ds_write_b32 v12, v14
	s_nop 1
	v_readlane_b32 s20, v14, 0
	v_readlane_b32 s21, v14, 1
	v_readlane_b32 s22, v14, 2
	v_readlane_b32 s23, v14, 3
	v_readlane_b32 s24, v14, 4
	v_readlane_b32 s25, v14, 5
	v_readlane_b32 s26, v14, 6
	v_readlane_b32 s27, v14, 7
	s_lshl_b32 s53, s12, 2
	v_subrev_u32_e32 v216, s53, v12
	ds_read_b32 v217, v216
	v_add_u32_e32 v218, s15, v13
	v_cmp_le_u32_e32 vcc, s12, v218
	v_add_u32_e32 v218, 1, v218
	v_min_u32_e32 v218, s12, v218
	v_cvt_f32_u32_e32 v220, v218
	s_waitcnt lgkmcnt(0)
	v_cndmask_b32_e32 v217, 0, v217, vcc
	s_nop 1
	v_readlane_b32 s36, v217, 0
	v_readlane_b32 s37, v217, 1
	v_readlane_b32 s38, v217, 2
	v_readlane_b32 s39, v217, 3
	v_readlane_b32 s40, v217, 4
	v_readlane_b32 s41, v217, 5
	v_readlane_b32 s42, v217, 6
	v_readlane_b32 s43, v217, 7
	v_div_scale_f32 v15, s[30:31], v220, v220, 1.0
	v_rcp_f32_e32 v216, v15
	v_div_scale_f32 v217, vcc, 1.0, v220, 1.0
	v_fma_f32 v218, -v15, v216, 1.0
	v_fmac_f32_e32 v216, v218, v216
	v_mul_f32_e32 v218, v217, v216
	v_fma_f32 v221, -v15, v218, v217
	v_fmac_f32_e32 v218, v221, v216
	v_fma_f32 v15, -v15, v218, v217
	v_div_fmas_f32 v15, v15, v216, v218
	v_div_fixup_f32 v14, v15, v220, 1.0
	s_nop 1
	v_readlane_b32 s44, v14, 0
	v_readlane_b32 s45, v14, 1
	v_readlane_b32 s46, v14, 2
	v_readlane_b32 s47, v14, 3
	v_readlane_b32 s48, v14, 4
	v_readlane_b32 s49, v14, 5
	v_readlane_b32 s50, v14, 6
	v_readlane_b32 s51, v14, 7
	s_nop 1
	s_add_i32 s52, s14, 0
	s_sub_i32 s52, s52, s12
	s_max_i32 s52, s52, 0
	s_mov_b32 s53, 0
	s_lshl_b64 s[52:53], s[52:53], 14
	s_add_u32 s52, s52, s2
	s_addc_u32 s53, s53, s3
	global_load_dwordx4 v[144:147], v1, s[52:53]
	global_load_dwordx4 v[148:151], v1, s[52:53] offset:1024
	s_add_i32 s52, s14, 1
	s_sub_i32 s52, s52, s12
	s_max_i32 s52, s52, 0
	s_mov_b32 s53, 0
	s_lshl_b64 s[52:53], s[52:53], 14
	s_add_u32 s52, s52, s2
	s_addc_u32 s53, s53, s3
	global_load_dwordx4 v[152:155], v1, s[52:53]
	global_load_dwordx4 v[156:159], v1, s[52:53] offset:1024
	s_add_i32 s52, s14, 2
	s_sub_i32 s52, s52, s12
	s_max_i32 s52, s52, 0
	s_mov_b32 s53, 0
	s_lshl_b64 s[52:53], s[52:53], 14
	s_add_u32 s52, s52, s2
	s_addc_u32 s53, s53, s3
	global_load_dwordx4 v[160:163], v1, s[52:53]
	global_load_dwordx4 v[164:167], v1, s[52:53] offset:1024
	s_add_i32 s52, s14, 3
	s_sub_i32 s52, s52, s12
	s_max_i32 s52, s52, 0
	s_mov_b32 s53, 0
	s_lshl_b64 s[52:53], s[52:53], 14
	s_add_u32 s52, s52, s2
	s_addc_u32 s53, s53, s3
	global_load_dwordx4 v[168:171], v1, s[52:53]
	global_load_dwordx4 v[172:175], v1, s[52:53] offset:1024
	s_add_i32 s52, s14, 4
	s_sub_i32 s52, s52, s12
	s_max_i32 s52, s52, 0
	s_mov_b32 s53, 0
	s_lshl_b64 s[52:53], s[52:53], 14
	s_add_u32 s52, s52, s2
	s_addc_u32 s53, s53, s3
	global_load_dwordx4 v[176:179], v1, s[52:53]
	global_load_dwordx4 v[180:183], v1, s[52:53] offset:1024
	s_add_i32 s52, s14, 5
	s_sub_i32 s52, s52, s12
	s_max_i32 s52, s52, 0
	s_mov_b32 s53, 0
	s_lshl_b64 s[52:53], s[52:53], 14
	s_add_u32 s52, s52, s2
	s_addc_u32 s53, s53, s3
	global_load_dwordx4 v[184:187], v1, s[52:53]
	global_load_dwordx4 v[188:191], v1, s[52:53] offset:1024
	s_add_i32 s52, s14, 6
	s_sub_i32 s52, s52, s12
	s_max_i32 s52, s52, 0
	s_mov_b32 s53, 0
	s_lshl_b64 s[52:53], s[52:53], 14
	s_add_u32 s52, s52, s2
	s_addc_u32 s53, s53, s3
	global_load_dwordx4 v[192:195], v1, s[52:53]
	global_load_dwordx4 v[196:199], v1, s[52:53] offset:1024
	s_add_i32 s52, s14, 7
	s_sub_i32 s52, s52, s12
	s_max_i32 s52, s52, 0
	s_mov_b32 s53, 0
	s_lshl_b64 s[52:53], s[52:53], 14
	s_add_u32 s52, s52, s2
	s_addc_u32 s53, s53, s3
	global_load_dwordx4 v[200:203], v1, s[52:53]
	global_load_dwordx4 v[204:207], v1, s[52:53] offset:1024
	s_cmp_ge_u32 s13, 9
	s_cbranch_scc1 .Lp1f_nonext_m1
	s_add_i32 s55, s14, 8
	s_add_i32 s52, s55, 0
	s_mov_b32 s53, 0
	s_lshl_b64 s[52:53], s[52:53], 14
	s_add_u32 s52, s52, s2
	s_addc_u32 s53, s53, s3
	global_load_dwordx4 v[16:19], v1, s[52:53]
	global_load_dwordx4 v[20:23], v1, s[52:53] offset:1024
	s_add_i32 s52, s55, 1
	s_mov_b32 s53, 0
	s_lshl_b64 s[52:53], s[52:53], 14
	s_add_u32 s52, s52, s2
	s_addc_u32 s53, s53, s3
	global_load_dwordx4 v[24:27], v1, s[52:53]
	global_load_dwordx4 v[28:31], v1, s[52:53] offset:1024
	s_add_i32 s52, s55, 2
	s_mov_b32 s53, 0
	s_lshl_b64 s[52:53], s[52:53], 14
	s_add_u32 s52, s52, s2
	s_addc_u32 s53, s53, s3
	global_load_dwordx4 v[32:35], v1, s[52:53]
	global_load_dwordx4 v[36:39], v1, s[52:53] offset:1024
	s_add_i32 s52, s55, 3
	s_mov_b32 s53, 0
	s_lshl_b64 s[52:53], s[52:53], 14
	s_add_u32 s52, s52, s2
	s_addc_u32 s53, s53, s3
	global_load_dwordx4 v[40:43], v1, s[52:53]
	global_load_dwordx4 v[44:47], v1, s[52:53] offset:1024
	s_add_i32 s52, s55, 4
	s_mov_b32 s53, 0
	s_lshl_b64 s[52:53], s[52:53], 14
	s_add_u32 s52, s52, s2
	s_addc_u32 s53, s53, s3
	global_load_dwordx4 v[48:51], v1, s[52:53]
	global_load_dwordx4 v[52:55], v1, s[52:53] offset:1024
	s_add_i32 s52, s55, 5
	s_mov_b32 s53, 0
	s_lshl_b64 s[52:53], s[52:53], 14
	s_add_u32 s52, s52, s2
	s_addc_u32 s53, s53, s3
	global_load_dwordx4 v[56:59], v1, s[52:53]
	global_load_dwordx4 v[60:63], v1, s[52:53] offset:1024
	s_add_i32 s52, s55, 6
	s_mov_b32 s53, 0
	s_lshl_b64 s[52:53], s[52:53], 14
	s_add_u32 s52, s52, s2
	s_addc_u32 s53, s53, s3
	global_load_dwordx4 v[64:67], v1, s[52:53]
	global_load_dwordx4 v[68:71], v1, s[52:53] offset:1024
	s_add_i32 s52, s55, 7
	s_mov_b32 s53, 0
	s_lshl_b64 s[52:53], s[52:53], 14
	s_add_u32 s52, s52, s2
	s_addc_u32 s53, s53, s3
	global_load_dwordx4 v[72:75], v1, s[52:53]
	global_load_dwordx4 v[76:79], v1, s[52:53] offset:1024
.Lp1f_nonext_m1:
	v_mul_f32_e32 v80, s20, v80
	v_mul_f32_e32 v81, s20, v81
	v_mul_f32_e32 v82, s20, v82
	v_mul_f32_e32 v83, s20, v83
	v_mul_f32_e32 v84, s20, v84
	v_mul_f32_e32 v85, s20, v85
	v_mul_f32_e32 v86, s20, v86
	v_mul_f32_e32 v87, s20, v87
	v_pk_mul_f32 v[80:81], v[80:81], v[4:5]
	v_pk_mul_f32 v[82:83], v[82:83], v[6:7]
	v_pk_mul_f32 v[84:85], v[84:85], v[8:9]
	v_pk_mul_f32 v[86:87], v[86:87], v[10:11]
	v_mul_f32_e32 v88, s21, v88
	v_mul_f32_e32 v89, s21, v89
	v_mul_f32_e32 v90, s21, v90
	v_mul_f32_e32 v91, s21, v91
	v_mul_f32_e32 v92, s21, v92
	v_mul_f32_e32 v93, s21, v93
	v_mul_f32_e32 v94, s21, v94
	v_mul_f32_e32 v95, s21, v95
	v_pk_mul_f32 v[88:89], v[88:89], v[4:5]
	v_pk_mul_f32 v[90:91], v[90:91], v[6:7]
	v_pk_mul_f32 v[92:93], v[92:93], v[8:9]
	v_pk_mul_f32 v[94:95], v[94:95], v[10:11]
	v_mul_f32_e32 v96, s22, v96
	v_mul_f32_e32 v97, s22, v97
	v_mul_f32_e32 v98, s22, v98
	v_mul_f32_e32 v99, s22, v99
	v_mul_f32_e32 v100, s22, v100
	v_mul_f32_e32 v101, s22, v101
	v_mul_f32_e32 v102, s22, v102
	v_mul_f32_e32 v103, s22, v103
	v_pk_mul_f32 v[96:97], v[96:97], v[4:5]
	v_pk_mul_f32 v[98:99], v[98:99], v[6:7]
	v_pk_mul_f32 v[100:101], v[100:101], v[8:9]
	v_pk_mul_f32 v[102:103], v[102:103], v[10:11]
	v_mul_f32_e32 v104, s23, v104
	v_mul_f32_e32 v105, s23, v105
	v_mul_f32_e32 v106, s23, v106
	v_mul_f32_e32 v107, s23, v107
	v_mul_f32_e32 v108, s23, v108
	v_mul_f32_e32 v109, s23, v109
	v_mul_f32_e32 v110, s23, v110
	v_mul_f32_e32 v111, s23, v111
	v_pk_mul_f32 v[104:105], v[104:105], v[4:5]
	v_pk_mul_f32 v[106:107], v[106:107], v[6:7]
	v_pk_mul_f32 v[108:109], v[108:109], v[8:9]
	v_pk_mul_f32 v[110:111], v[110:111], v[10:11]
	v_mul_f32_e32 v112, s24, v112
	v_mul_f32_e32 v113, s24, v113
	v_mul_f32_e32 v114, s24, v114
	v_mul_f32_e32 v115, s24, v115
	v_mul_f32_e32 v116, s24, v116
	v_mul_f32_e32 v117, s24, v117
	v_mul_f32_e32 v118, s24, v118
	v_mul_f32_e32 v119, s24, v119
	v_pk_mul_f32 v[112:113], v[112:113], v[4:5]
	v_pk_mul_f32 v[114:115], v[114:115], v[6:7]
	v_pk_mul_f32 v[116:117], v[116:117], v[8:9]
	v_pk_mul_f32 v[118:119], v[118:119], v[10:11]
	v_mul_f32_e32 v120, s25, v120
	v_mul_f32_e32 v121, s25, v121
	v_mul_f32_e32 v122, s25, v122
	v_mul_f32_e32 v123, s25, v123
	v_mul_f32_e32 v124, s25, v124
	v_mul_f32_e32 v125, s25, v125
	v_mul_f32_e32 v126, s25, v126
	v_mul_f32_e32 v127, s25, v127
	v_pk_mul_f32 v[120:121], v[120:121], v[4:5]
	v_pk_mul_f32 v[122:123], v[122:123], v[6:7]
	v_pk_mul_f32 v[124:125], v[124:125], v[8:9]
	v_pk_mul_f32 v[126:127], v[126:127], v[10:11]
	v_mul_f32_e32 v128, s26, v128
	v_mul_f32_e32 v129, s26, v129
	v_mul_f32_e32 v130, s26, v130
	v_mul_f32_e32 v131, s26, v131
	v_mul_f32_e32 v132, s26, v132
	v_mul_f32_e32 v133, s26, v133
	v_mul_f32_e32 v134, s26, v134
	v_mul_f32_e32 v135, s26, v135
	v_pk_mul_f32 v[128:129], v[128:129], v[4:5]
	v_pk_mul_f32 v[130:131], v[130:131], v[6:7]
	v_pk_mul_f32 v[132:133], v[132:133], v[8:9]
	v_pk_mul_f32 v[134:135], v[134:135], v[10:11]
	v_mul_f32_e32 v136, s27, v136
	v_mul_f32_e32 v137, s27, v137
	v_mul_f32_e32 v138, s27, v138
	v_mul_f32_e32 v139, s27, v139
	v_mul_f32_e32 v140, s27, v140
	v_mul_f32_e32 v141, s27, v141
	v_mul_f32_e32 v142, s27, v142
	v_mul_f32_e32 v143, s27, v143
	v_pk_mul_f32 v[136:137], v[136:137], v[4:5]
	v_pk_mul_f32 v[138:139], v[138:139], v[6:7]
	v_pk_mul_f32 v[140:141], v[140:141], v[8:9]
	v_pk_mul_f32 v[142:143], v[142:143], v[10:11]
	s_cmp_ge_u32 s13, 9
	s_cbranch_scc1 .Lp1f_w0_m1
	s_waitcnt vmcnt(16)
	s_branch .Lp1f_w1_m1

.Lp1f_w1_m1:
	v_mul_f32_e32 v144, s36, v144
	v_mul_f32_e32 v145, s36, v145
	v_mul_f32_e32 v146, s36, v146
	v_mul_f32_e32 v147, s36, v147
	v_mul_f32_e32 v148, s36, v148
	v_mul_f32_e32 v149, s36, v149
	v_mul_f32_e32 v150, s36, v150
	v_mul_f32_e32 v151, s36, v151
	v_pk_mul_f32 v[144:145], v[144:145], v[4:5]
	v_pk_mul_f32 v[146:147], v[146:147], v[6:7]
	v_pk_mul_f32 v[148:149], v[148:149], v[8:9]
	v_pk_mul_f32 v[150:151], v[150:151], v[10:11]
	v_mul_f32_e32 v152, s37, v152
	v_mul_f32_e32 v153, s37, v153
	v_mul_f32_e32 v154, s37, v154
	v_mul_f32_e32 v155, s37, v155
	v_mul_f32_e32 v156, s37, v156
	v_mul_f32_e32 v157, s37, v157
	v_mul_f32_e32 v158, s37, v158
	v_mul_f32_e32 v159, s37, v159
	v_pk_mul_f32 v[152:153], v[152:153], v[4:5]
	v_pk_mul_f32 v[154:155], v[154:155], v[6:7]
	v_pk_mul_f32 v[156:157], v[156:157], v[8:9]
	v_pk_mul_f32 v[158:159], v[158:159], v[10:11]
	v_mul_f32_e32 v160, s38, v160
	v_mul_f32_e32 v161, s38, v161
	v_mul_f32_e32 v162, s38, v162
	v_mul_f32_e32 v163, s38, v163
	v_mul_f32_e32 v164, s38, v164
	v_mul_f32_e32 v165, s38, v165
	v_mul_f32_e32 v166, s38, v166
	v_mul_f32_e32 v167, s38, v167
	v_pk_mul_f32 v[160:161], v[160:161], v[4:5]
	v_pk_mul_f32 v[162:163], v[162:163], v[6:7]
	v_pk_mul_f32 v[164:165], v[164:165], v[8:9]
	v_pk_mul_f32 v[166:167], v[166:167], v[10:11]
	v_mul_f32_e32 v168, s39, v168
	v_mul_f32_e32 v169, s39, v169
	v_mul_f32_e32 v170, s39, v170
	v_mul_f32_e32 v171, s39, v171
	v_mul_f32_e32 v172, s39, v172
	v_mul_f32_e32 v173, s39, v173
	v_mul_f32_e32 v174, s39, v174
	v_mul_f32_e32 v175, s39, v175
	v_pk_mul_f32 v[168:169], v[168:169], v[4:5]
	v_pk_mul_f32 v[170:171], v[170:171], v[6:7]
	v_pk_mul_f32 v[172:173], v[172:173], v[8:9]
	v_pk_mul_f32 v[174:175], v[174:175], v[10:11]
	v_mul_f32_e32 v176, s40, v176
	v_mul_f32_e32 v177, s40, v177
	v_mul_f32_e32 v178, s40, v178
	v_mul_f32_e32 v179, s40, v179
	v_mul_f32_e32 v180, s40, v180
	v_mul_f32_e32 v181, s40, v181
	v_mul_f32_e32 v182, s40, v182
	v_mul_f32_e32 v183, s40, v183
	v_pk_mul_f32 v[176:177], v[176:177], v[4:5]
	v_pk_mul_f32 v[178:179], v[178:179], v[6:7]
	v_pk_mul_f32 v[180:181], v[180:181], v[8:9]
	v_pk_mul_f32 v[182:183], v[182:183], v[10:11]
	v_mul_f32_e32 v184, s41, v184
	v_mul_f32_e32 v185, s41, v185
	v_mul_f32_e32 v186, s41, v186
	v_mul_f32_e32 v187, s41, v187
	v_mul_f32_e32 v188, s41, v188
	v_mul_f32_e32 v189, s41, v189
	v_mul_f32_e32 v190, s41, v190
	v_mul_f32_e32 v191, s41, v191
	v_pk_mul_f32 v[184:185], v[184:185], v[4:5]
	v_pk_mul_f32 v[186:187], v[186:187], v[6:7]
	v_pk_mul_f32 v[188:189], v[188:189], v[8:9]
	v_pk_mul_f32 v[190:191], v[190:191], v[10:11]
	v_mul_f32_e32 v192, s42, v192
	v_mul_f32_e32 v193, s42, v193
	v_mul_f32_e32 v194, s42, v194
	v_mul_f32_e32 v195, s42, v195
	v_mul_f32_e32 v196, s42, v196
	v_mul_f32_e32 v197, s42, v197
	v_mul_f32_e32 v198, s42, v198
	v_mul_f32_e32 v199, s42, v199
	v_pk_mul_f32 v[192:193], v[192:193], v[4:5]
	v_pk_mul_f32 v[194:195], v[194:195], v[6:7]
	v_pk_mul_f32 v[196:197], v[196:197], v[8:9]
	v_pk_mul_f32 v[198:199], v[198:199], v[10:11]
	v_mul_f32_e32 v200, s43, v200
	v_mul_f32_e32 v201, s43, v201
	v_mul_f32_e32 v202, s43, v202
	v_mul_f32_e32 v203, s43, v203
	v_mul_f32_e32 v204, s43, v204
	v_mul_f32_e32 v205, s43, v205
	v_mul_f32_e32 v206, s43, v206
	v_mul_f32_e32 v207, s43, v207
	v_pk_mul_f32 v[200:201], v[200:201], v[4:5]
	v_pk_mul_f32 v[202:203], v[202:203], v[6:7]
	v_pk_mul_f32 v[204:205], v[204:205], v[8:9]
	v_pk_mul_f32 v[206:207], v[206:207], v[10:11]
	v_pk_add_f32 v[208:209], v[208:209], v[80:81]
	v_pk_add_f32 v[210:211], v[210:211], v[82:83]
	v_pk_add_f32 v[212:213], v[212:213], v[84:85]
	v_pk_add_f32 v[214:215], v[214:215], v[86:87]
	v_pk_add_f32 v[208:209], v[208:209], v[144:145] neg_lo:[0,1] neg_hi:[0,1]
	v_pk_add_f32 v[210:211], v[210:211], v[146:147] neg_lo:[0,1] neg_hi:[0,1]
	v_pk_add_f32 v[212:213], v[212:213], v[148:149] neg_lo:[0,1] neg_hi:[0,1]
	v_pk_add_f32 v[214:215], v[214:215], v[150:151] neg_lo:[0,1] neg_hi:[0,1]
	v_fma_f32 v12, v208, s44, -v80
	v_fma_f32 v13, v209, s44, -v81
	v_fma_f32 v14, v210, s44, -v82
	v_fma_f32 v15, v211, s44, -v83
	v_fma_f32 v216, v212, s44, -v84
	v_fma_f32 v217, v213, s44, -v85
	v_fma_f32 v218, v214, s44, -v86
	v_fma_f32 v220, v215, s44, -v87
	v_cvt_pk_bf16_f32 v144, v12, v13
	v_cvt_pk_bf16_f32 v145, v14, v15
	v_cvt_pk_bf16_f32 v146, v216, v217
	v_cvt_pk_bf16_f32 v147, v218, v220
	s_add_i32 s52, s14, 0
	s_mov_b32 s53, 0
	s_lshl_b64 s[52:53], s[52:53], 13
	s_add_u32 s52, s52, s4
	s_addc_u32 s53, s53, s5
	global_store_dwordx2 v3, v[144:145], s[52:53]
	global_store_dwordx2 v3, v[146:147], s[52:53] offset:512
	v_pk_add_f32 v[208:209], v[208:209], v[88:89]
	v_pk_add_f32 v[210:211], v[210:211], v[90:91]
	v_pk_add_f32 v[212:213], v[212:213], v[92:93]
	v_pk_add_f32 v[214:215], v[214:215], v[94:95]
	v_pk_add_f32 v[208:209], v[208:209], v[152:153] neg_lo:[0,1] neg_hi:[0,1]
	v_pk_add_f32 v[210:211], v[210:211], v[154:155] neg_lo:[0,1] neg_hi:[0,1]
	v_pk_add_f32 v[212:213], v[212:213], v[156:157] neg_lo:[0,1] neg_hi:[0,1]
	v_pk_add_f32 v[214:215], v[214:215], v[158:159] neg_lo:[0,1] neg_hi:[0,1]
	v_fma_f32 v12, v208, s45, -v88
	v_fma_f32 v13, v209, s45, -v89
	v_fma_f32 v14, v210, s45, -v90
	v_fma_f32 v15, v211, s45, -v91
	v_fma_f32 v216, v212, s45, -v92
	v_fma_f32 v217, v213, s45, -v93
	v_fma_f32 v218, v214, s45, -v94
	v_fma_f32 v220, v215, s45, -v95
	v_cvt_pk_bf16_f32 v152, v12, v13
	v_cvt_pk_bf16_f32 v153, v14, v15
	v_cvt_pk_bf16_f32 v154, v216, v217
	v_cvt_pk_bf16_f32 v155, v218, v220
	s_add_i32 s52, s14, 1
	s_mov_b32 s53, 0
	s_lshl_b64 s[52:53], s[52:53], 13
	s_add_u32 s52, s52, s4
	s_addc_u32 s53, s53, s5
	global_store_dwordx2 v3, v[152:153], s[52:53]
	global_store_dwordx2 v3, v[154:155], s[52:53] offset:512
	v_pk_add_f32 v[208:209], v[208:209], v[96:97]
	v_pk_add_f32 v[210:211], v[210:211], v[98:99]
	v_pk_add_f32 v[212:213], v[212:213], v[100:101]
	v_pk_add_f32 v[214:215], v[214:215], v[102:103]
	v_pk_add_f32 v[208:209], v[208:209], v[160:161] neg_lo:[0,1] neg_hi:[0,1]
	v_pk_add_f32 v[210:211], v[210:211], v[162:163] neg_lo:[0,1] neg_hi:[0,1]
	v_pk_add_f32 v[212:213], v[212:213], v[164:165] neg_lo:[0,1] neg_hi:[0,1]
	v_pk_add_f32 v[214:215], v[214:215], v[166:167] neg_lo:[0,1] neg_hi:[0,1]
	v_fma_f32 v12, v208, s46, -v96
	v_fma_f32 v13, v209, s46, -v97
	v_fma_f32 v14, v210, s46, -v98
	v_fma_f32 v15, v211, s46, -v99
	v_fma_f32 v216, v212, s46, -v100
	v_fma_f32 v217, v213, s46, -v101
	v_fma_f32 v218, v214, s46, -v102
	v_fma_f32 v220, v215, s46, -v103
	v_cvt_pk_bf16_f32 v160, v12, v13
	v_cvt_pk_bf16_f32 v161, v14, v15
	v_cvt_pk_bf16_f32 v162, v216, v217
	v_cvt_pk_bf16_f32 v163, v218, v220
	s_add_i32 s52, s14, 2
	s_mov_b32 s53, 0
	s_lshl_b64 s[52:53], s[52:53], 13
	s_add_u32 s52, s52, s4
	s_addc_u32 s53, s53, s5
	global_store_dwordx2 v3, v[160:161], s[52:53]
	global_store_dwordx2 v3, v[162:163], s[52:53] offset:512
	v_pk_add_f32 v[208:209], v[208:209], v[104:105]
	v_pk_add_f32 v[210:211], v[210:211], v[106:107]
	v_pk_add_f32 v[212:213], v[212:213], v[108:109]
	v_pk_add_f32 v[214:215], v[214:215], v[110:111]
	v_pk_add_f32 v[208:209], v[208:209], v[168:169] neg_lo:[0,1] neg_hi:[0,1]
	v_pk_add_f32 v[210:211], v[210:211], v[170:171] neg_lo:[0,1] neg_hi:[0,1]
	v_pk_add_f32 v[212:213], v[212:213], v[172:173] neg_lo:[0,1] neg_hi:[0,1]
	v_pk_add_f32 v[214:215], v[214:215], v[174:175] neg_lo:[0,1] neg_hi:[0,1]
	v_fma_f32 v12, v208, s47, -v104
	v_fma_f32 v13, v209, s47, -v105
	v_fma_f32 v14, v210, s47, -v106
	v_fma_f32 v15, v211, s47, -v107
	v_fma_f32 v216, v212, s47, -v108
	v_fma_f32 v217, v213, s47, -v109
	v_fma_f32 v218, v214, s47, -v110
	v_fma_f32 v220, v215, s47, -v111
	v_cvt_pk_bf16_f32 v168, v12, v13
	v_cvt_pk_bf16_f32 v169, v14, v15
	v_cvt_pk_bf16_f32 v170, v216, v217
	v_cvt_pk_bf16_f32 v171, v218, v220
	s_add_i32 s52, s14, 3
	s_mov_b32 s53, 0
	s_lshl_b64 s[52:53], s[52:53], 13
	s_add_u32 s52, s52, s4
	s_addc_u32 s53, s53, s5
	global_store_dwordx2 v3, v[168:169], s[52:53]
	global_store_dwordx2 v3, v[170:171], s[52:53] offset:512
	v_pk_add_f32 v[208:209], v[208:209], v[112:113]
	v_pk_add_f32 v[210:211], v[210:211], v[114:115]
	v_pk_add_f32 v[212:213], v[212:213], v[116:117]
	v_pk_add_f32 v[214:215], v[214:215], v[118:119]
	v_pk_add_f32 v[208:209], v[208:209], v[176:177] neg_lo:[0,1] neg_hi:[0,1]
	v_pk_add_f32 v[210:211], v[210:211], v[178:179] neg_lo:[0,1] neg_hi:[0,1]
	v_pk_add_f32 v[212:213], v[212:213], v[180:181] neg_lo:[0,1] neg_hi:[0,1]
	v_pk_add_f32 v[214:215], v[214:215], v[182:183] neg_lo:[0,1] neg_hi:[0,1]
	v_fma_f32 v12, v208, s48, -v112
	v_fma_f32 v13, v209, s48, -v113
	v_fma_f32 v14, v210, s48, -v114
	v_fma_f32 v15, v211, s48, -v115
	v_fma_f32 v216, v212, s48, -v116
	v_fma_f32 v217, v213, s48, -v117
	v_fma_f32 v218, v214, s48, -v118
	v_fma_f32 v220, v215, s48, -v119
	v_cvt_pk_bf16_f32 v176, v12, v13
	v_cvt_pk_bf16_f32 v177, v14, v15
	v_cvt_pk_bf16_f32 v178, v216, v217
	v_cvt_pk_bf16_f32 v179, v218, v220
	s_add_i32 s52, s14, 4
	s_mov_b32 s53, 0
	s_lshl_b64 s[52:53], s[52:53], 13
	s_add_u32 s52, s52, s4
	s_addc_u32 s53, s53, s5
	global_store_dwordx2 v3, v[176:177], s[52:53]
	global_store_dwordx2 v3, v[178:179], s[52:53] offset:512
	v_pk_add_f32 v[208:209], v[208:209], v[120:121]
	v_pk_add_f32 v[210:211], v[210:211], v[122:123]
	v_pk_add_f32 v[212:213], v[212:213], v[124:125]
	v_pk_add_f32 v[214:215], v[214:215], v[126:127]
	v_pk_add_f32 v[208:209], v[208:209], v[184:185] neg_lo:[0,1] neg_hi:[0,1]
	v_pk_add_f32 v[210:211], v[210:211], v[186:187] neg_lo:[0,1] neg_hi:[0,1]
	v_pk_add_f32 v[212:213], v[212:213], v[188:189] neg_lo:[0,1] neg_hi:[0,1]
	v_pk_add_f32 v[214:215], v[214:215], v[190:191] neg_lo:[0,1] neg_hi:[0,1]
	v_fma_f32 v12, v208, s49, -v120
	v_fma_f32 v13, v209, s49, -v121
	v_fma_f32 v14, v210, s49, -v122
	v_fma_f32 v15, v211, s49, -v123
	v_fma_f32 v216, v212, s49, -v124
	v_fma_f32 v217, v213, s49, -v125
	v_fma_f32 v218, v214, s49, -v126
	v_fma_f32 v220, v215, s49, -v127
	v_cvt_pk_bf16_f32 v184, v12, v13
	v_cvt_pk_bf16_f32 v185, v14, v15
	v_cvt_pk_bf16_f32 v186, v216, v217
	v_cvt_pk_bf16_f32 v187, v218, v220
	s_add_i32 s52, s14, 5
	s_mov_b32 s53, 0
	s_lshl_b64 s[52:53], s[52:53], 13
	s_add_u32 s52, s52, s4
	s_addc_u32 s53, s53, s5
	global_store_dwordx2 v3, v[184:185], s[52:53]
	global_store_dwordx2 v3, v[186:187], s[52:53] offset:512
	v_pk_add_f32 v[208:209], v[208:209], v[128:129]
	v_pk_add_f32 v[210:211], v[210:211], v[130:131]
	v_pk_add_f32 v[212:213], v[212:213], v[132:133]
	v_pk_add_f32 v[214:215], v[214:215], v[134:135]
	v_pk_add_f32 v[208:209], v[208:209], v[192:193] neg_lo:[0,1] neg_hi:[0,1]
	v_pk_add_f32 v[210:211], v[210:211], v[194:195] neg_lo:[0,1] neg_hi:[0,1]
	v_pk_add_f32 v[212:213], v[212:213], v[196:197] neg_lo:[0,1] neg_hi:[0,1]
	v_pk_add_f32 v[214:215], v[214:215], v[198:199] neg_lo:[0,1] neg_hi:[0,1]
	v_fma_f32 v12, v208, s50, -v128
	v_fma_f32 v13, v209, s50, -v129
	v_fma_f32 v14, v210, s50, -v130
	v_fma_f32 v15, v211, s50, -v131
	v_fma_f32 v216, v212, s50, -v132
	v_fma_f32 v217, v213, s50, -v133
	v_fma_f32 v218, v214, s50, -v134
	v_fma_f32 v220, v215, s50, -v135
	v_cvt_pk_bf16_f32 v192, v12, v13
	v_cvt_pk_bf16_f32 v193, v14, v15
	v_cvt_pk_bf16_f32 v194, v216, v217
	v_cvt_pk_bf16_f32 v195, v218, v220
	s_add_i32 s52, s14, 6
	s_mov_b32 s53, 0
	s_lshl_b64 s[52:53], s[52:53], 13
	s_add_u32 s52, s52, s4
	s_addc_u32 s53, s53, s5
	global_store_dwordx2 v3, v[192:193], s[52:53]
	global_store_dwordx2 v3, v[194:195], s[52:53] offset:512
	v_pk_add_f32 v[208:209], v[208:209], v[136:137]
	v_pk_add_f32 v[210:211], v[210:211], v[138:139]
	v_pk_add_f32 v[212:213], v[212:213], v[140:141]
	v_pk_add_f32 v[214:215], v[214:215], v[142:143]
	v_pk_add_f32 v[208:209], v[208:209], v[200:201] neg_lo:[0,1] neg_hi:[0,1]
	v_pk_add_f32 v[210:211], v[210:211], v[202:203] neg_lo:[0,1] neg_hi:[0,1]
	v_pk_add_f32 v[212:213], v[212:213], v[204:205] neg_lo:[0,1] neg_hi:[0,1]
	v_pk_add_f32 v[214:215], v[214:215], v[206:207] neg_lo:[0,1] neg_hi:[0,1]
	v_fma_f32 v12, v208, s51, -v136
	v_fma_f32 v13, v209, s51, -v137
	v_fma_f32 v14, v210, s51, -v138
	v_fma_f32 v15, v211, s51, -v139
	v_fma_f32 v216, v212, s51, -v140
	v_fma_f32 v217, v213, s51, -v141
	v_fma_f32 v218, v214, s51, -v142
	v_fma_f32 v220, v215, s51, -v143
	v_cvt_pk_bf16_f32 v200, v12, v13
	v_cvt_pk_bf16_f32 v201, v14, v15
	v_cvt_pk_bf16_f32 v202, v216, v217
	v_cvt_pk_bf16_f32 v203, v218, v220
	s_add_i32 s52, s14, 7
	s_mov_b32 s53, 0
	s_lshl_b64 s[52:53], s[52:53], 13
	s_add_u32 s52, s52, s4
	s_addc_u32 s53, s53, s5
	global_store_dwordx2 v3, v[200:201], s[52:53]
	global_store_dwordx2 v3, v[202:203], s[52:53] offset:512
	s_add_i32 s13, s13, 1
	s_add_i32 s14, s14, 8
	s_add_i32 s15, s15, 8
	s_cmp_lt_u32 s13, 10
	s_cbranch_scc1 .Lp1f_loop
